# speedup vs baseline: 1.0132x; 1.0132x over previous
; DI int my_tid() { int t = threadIdx.x; asm volatile("" : "+v"(t)); return t; }
; DI int my_block() { int b = blockIdx.x; asm volatile("" : "+s"(b)); return b; }
; #define G_STAGE(bufoff, gbase, voff) do { _Pragma("unroll") for (int _i = 0; _i < 2; ++_i) \
;         __builtin_amdgcn_global_load_lds((const unsigned*)((const char*)(gbase) + (voff)[_i]), (LAS unsigned*)(lds + (bufoff) + ldsw + _i * 8192), 16, 0, 0); } while (0)
; #define G_BAR __builtin_amdgcn_s_barrier()
;   DI int brow_of(int R) const { return (R & ~31) + perm32(R & 31); }
; template <class J>
; DI void gemm_phase(LAS unsigned char* lds, const J& job) {
;   const int tid = my_tid(), wid = __builtin_amdgcn_readfirstlane(tid >> 6), lane = tid & 63, wr = wid >> 2, wc = wid & 3, fr = lane & 15, fq = lane >> 4;
;   const int nt = job.nt;
;   unsigned voffA[2], voffB[2];
; #pragma unroll
;   for (int i = 0; i < 2; ++i) { int R, C; stage_rc(tid * 16 + i * 8192, R, C); const int Rb = job.brow_of(R);
;     voffA[i] = (unsigned)(R * job.lda + C) * 2u; voffB[i] = (unsigned)(Rb * job.ldb + C) * 2u; }
;   const size_t kstep = (size_t)(BK * 2);
;   const size_t hstepA = (size_t)HALF * job.lda * 2, hstepB = (size_t)job.bhalf_rows() * job.ldb * 2;
;   const unsigned ldsw = (unsigned)wid * 1024u;
;   const int aoff = lds_byte(wr * 64 + fr, fq * 8), boff = lds_byte(wc * 32 + fr, fq * 8);
;     ...
;   Unit cur, nxt; int ui = 0;
;   if (!job.next(0, cur)) return;
;   f32x4 acc[2][2][4][2];
; #pragma unroll
;   for (int a = 0; a < 2; ++a)
; #pragma unroll
;     for (int b = 0; b < 2; ++b)
; #pragma unroll
;       for (int m = 0; m < 4; ++m)
; #pragma unroll
;         for (int n = 0; n < 2; ++n) acc[a][b][m][n] = (f32x4){0.f, 0.f, 0.f, 0.f};
;   bf16x8 At[4][2], B0[2][2], B1[2][2];
;   const char* cA = job.aptr(cur); const char* cB = job.bptr(cur);
;   const int koff = (my_block() & 7) * (nt >> 3), kmask = nt - 1;
;     ...
;   G_STAGE(G_SB(0, 0), cB + G_KT(0), voffB); G_STAGE(G_SA(0, 0), cA + G_KT(0), voffA); G_STAGE(G_SB(0, 1), cB + hstepB + G_KT(0), voffB); G_STAGE(G_SA(0, 1), cA + hstepA + G_KT(0), voffA);
;   if (wr == 1) G_BAR;
;     u.pn = ((((u.pn >> 2) + (c & 1)) & 1) << 2) + (u.pn & 3);
;     return true; }
;   DI const char* aptr(const Unit& u) const { return (const char*)(mixed + (size_t)u.pm * 256 * DM); }
;   DI const char* bptr(const Unit& u) const { return (const char*)(woutT + (size_t)u.pn * 256 * DM); }
.LBB0_32:
	v_bfe_i32 v3, v0, 27, 1
	v_lshlrev_b32_e32 v1, 4, v0
	v_lshrrev_b32_e32 v3, 22, v3
	v_writelane_b32 v255, s87, 22
	v_add_u32_e32 v3, v1, v3
	s_add_i32 s0, s4, s7
	s_ashr_i32 s5, s1, 8
	v_and_b32_e32 v3, 0xfffffc00, v3
	v_writelane_b32 v255, s1, 23
	s_ashr_i32 s6, s1, 6
	s_ashr_i32 s1, s0, 31
	v_ashrrev_i32_e32 v2, 31, v0
	v_sub_u32_e32 v3, v1, v3
	s_lshr_b32 s1, s1, 26
	v_lshrrev_b32_e32 v2, 26, v2
	s_waitcnt vmcnt(0)
	v_lshrrev_b32_e32 v4, 4, v3
	s_add_i32 s1, s0, s1
	v_add_u32_e32 v2, v0, v2
	v_bitop3_b32 v4, v4, v3, 32 bitop3:0x6c
	v_ashrrev_i32_e32 v3, 31, v3
	s_ashr_i32 s4, s1, 6
	s_and_b32 s1, s1, 0xffc0
	v_ashrrev_i32_e32 v2, 6, v2
	v_lshrrev_b32_e32 v3, 26, v3
	s_sub_i32 s0, s0, s1
	v_lshlrev_b32_e32 v5, 3, v2
	v_add_u32_e32 v3, v4, v3
	s_bfe_i32 s1, s0, 0x80000
	v_and_b32_e32 v5, -16, v5
	v_ashrrev_i32_e32 v3, 6, v3
	s_bfe_u32 s1, s1, 0x3000c
	v_add_u32_e32 v5, v3, v5
	v_mul_i32_i24_e32 v3, 64, v3
	s_add_i32 s1, s0, s1
	v_sub_u32_e32 v3, v4, v3
	s_lshl_b32 s15, s4, 3
	s_bfe_i32 s4, s1, 0x80000
	s_and_b32 s1, s1, 0xf8
	v_lshlrev_b32_e32 v2, 5, v2
	v_ashrrev_i16_sdwa v3, v220, sext(v3) dst_sel:DWORD dst_unused:UNUSED_PAD src0_sel:DWORD src1_sel:BYTE_0
	v_lshlrev_b32_e32 v4, 1, v5
	v_lshrrev_b32_e32 v6, 2, v5
	s_sub_i32 s0, s0, s1
	v_and_b32_e32 v2, 32, v2
	v_bfe_i32 v3, v3, 0, 16
	v_and_b32_e32 v4, 24, v4
	v_and_b32_e32 v6, 4, v6
	v_and_b32_e32 v7, 0xfffe3, v5
	s_and_b32 s4, 0xffff, s4
	s_sext_i32_i8 s0, s0
	v_or3_b32 v4, v7, v6, v4
	v_add_lshl_u32 v2, v2, v3, 1
	v_add_u32_e32 v1, 0x2000, v1
	s_lshr_b32 s7, s4, 3
	s_add_i32 s66, s15, s0
	s_lshl_b32 s15, s43, 2
	v_lshl_add_u32 v148, v5, 12, v2
	v_lshl_add_u32 v146, v4, 12, v2
	v_ashrrev_i32_e32 v2, 31, v1
	s_add_i32 s0, s15, s7
	v_lshrrev_b32_e32 v2, 22, v2
	s_and_b32 s0, s0, 4
	s_bfe_u32 s1, s4, 0x20003
	v_add_u32_e32 v2, v1, v2
	s_or_b32 s46, s0, s1
	s_ashr_i32 s67, s66, 31
	v_ashrrev_i32_e32 v2, 10, v2
	s_lshl_b32 s14, s6, 10
	s_lshl_b64 s[0:1], s[66:67], 20
	s_lshl_b32 s4, s46, 20
	v_mul_i32_i24_e32 v3, 0x400, v2
	s_add_u32 s68, s12, s4
	s_mov_b32 s4, s2
	v_sub_u32_e32 v1, v1, v3
	s_addc_u32 s69, s13, 0
	s_lshl_b32 s2, s4, 2
	v_lshrrev_b32_e32 v3, 4, v1
	s_and_b32 s2, s2, 28
	v_bitop3_b32 v1, v3, v1, 32 bitop3:0x6c
	s_lshl_b32 s24, s2, 7
	v_ashrrev_i32_e32 v4, 31, v1
	s_add_u32 s18, s68, s24
	v_lshrrev_b32_e32 v4, 26, v4
	s_addc_u32 s19, s69, 0
	s_add_i32 s25, s14, 0x100
	v_lshlrev_b32_e32 v3, 3, v2
	v_add_u32_e32 v4, v1, v4
	s_add_i32 m0, s25, 0x10000
	v_and_b32_e32 v3, -16, v3
	v_ashrrev_i32_e32 v5, 6, v4
	v_and_b32_e32 v4, 0xc0, v4
	global_load_lds_dwordx4 v146, s[18:19]
	s_add_i32 m0, s25, 0x12000
	v_add_u32_e32 v3, v5, v3
	v_sub_u32_e32 v1, v1, v4
	s_add_u32 s70, s10, s0
	v_lshlrev_b32_e32 v2, 5, v2
	v_ashrrev_i16_sdwa v1, v220, sext(v1) dst_sel:DWORD dst_unused:UNUSED_PAD src0_sel:DWORD src1_sel:BYTE_0
	v_lshlrev_b32_e32 v4, 1, v3
	v_lshrrev_b32_e32 v5, 2, v3
	s_addc_u32 s71, s11, s1
	v_and_b32_e32 v2, 32, v2
	v_bfe_i32 v1, v1, 0, 16
	v_and_b32_e32 v4, 24, v4
	v_and_b32_e32 v5, 4, v5
	v_and_b32_e32 v6, 0xfffe3, v3
	s_add_u32 s0, s70, s24
	v_or3_b32 v4, v6, v5, v4
	v_add_lshl_u32 v1, v2, v1, 1
	s_addc_u32 s1, s71, 0
	s_add_i32 s36, s25, 0x2000
	v_lshl_add_u32 v152, v4, 12, v1
	s_add_u32 s7, s68, 0x80000
	global_load_lds_dwordx4 v152, s[18:19]
	s_mov_b32 m0, s25
	s_addc_u32 s18, s69, 0
	v_lshl_add_u32 v150, v3, 12, v1
	global_load_lds_dwordx4 v148, s[0:1]
	s_mov_b32 m0, s36
	s_add_u32 s20, s7, s24
	global_load_lds_dwordx4 v150, s[0:1]
	s_addc_u32 s21, s18, 0
	s_add_i32 m0, s25, 0x14000
	s_nop 0
	global_load_lds_dwordx4 v146, s[20:21]
	s_add_i32 m0, s25, 0x16000
	s_add_u32 s0, s0, 0x80000
	s_addc_u32 s1, s1, 0
	s_add_i32 s37, s25, 0x4000
	global_load_lds_dwordx4 v152, s[20:21]
	s_mov_b32 m0, s37
	s_add_i32 s38, s25, 0x6000
	global_load_lds_dwordx4 v148, s[0:1]
	s_mov_b32 m0, s38
	s_cmp_lg_u32 s5, 1
	global_load_lds_dwordx4 v150, s[0:1]
	s_cbranch_scc1 .LBB0_34
	s_barrier
	s_setprio 1

; #define G_STAGE(bufoff, gbase, voff) do { _Pragma("unroll") for (int _i = 0; _i < 2; ++_i) \
;         __builtin_amdgcn_global_load_lds((const unsigned*)((const char*)(gbase) + (voff)[_i]), (LAS unsigned*)(lds + (bufoff) + ldsw + _i * 8192), 16, 0, 0); } while (0)
; #define G_LDA(dst, b, h) do { _Pragma("unroll") for (int m = 0; m < 4; ++m) _Pragma("unroll") for (int k = 0; k < 2; ++k) dst[m][k] = *(const LAS bf16x8*)(lds + G_SA(b, h) + aoff + m * 2048 + k * 1024); } while (0)
; #define G_LDB(dst, b, h) do { _Pragma("unroll") for (int n = 0; n < 2; ++n) _Pragma("unroll") for (int k = 0; k < 2; ++k) dst[n][k] = *(const LAS bf16x8*)(lds + G_SB(b, h) + boff + n * 2048 + k * 1024); } while (0)
; #define G_MMA(ai, bj, At, Bt) do { __builtin_amdgcn_s_setprio(1); _Pragma("unroll") for (int m = 0; m < 4; ++m) _Pragma("unroll") for (int n = 0; n < 2; ++n) _Pragma("unroll") for (int k = 0; k < 2; ++k) \
;         acc[ai][bj][m][n] = __builtin_amdgcn_mfma_f32_16x16x32_bf16(Bt[n][k], At[m][k], acc[ai][bj][m][n], 0, 0, 0); __builtin_amdgcn_s_setprio(0); } while (0)
; #define G_WAIT_L(n) asm volatile("s_waitcnt lgkmcnt(" #n ")" ::: "memory")
; #define G_BAR __builtin_amdgcn_s_barrier()
; #define G_SCHED __builtin_amdgcn_sched_barrier(0)
;   DI const char* aptr(const Unit& u) const { return (const char*)(h + (size_t)u.pm * 256 * DM); }
; template <class J>
; DI void gemm_phase(LAS unsigned char* lds, const J& job) {
;     ...
;     const bool has_next = job.next(ui + 1, nxt);
;     const char* nA = has_next ? job.aptr(nxt) : cA; const char* nB = has_next ? job.bptr(nxt) : cB;
;     for (int t = 0; t < nt; t += 2) {
;       const bool last = (t == nt - 2);
;       const char* a1 = cA + G_KT(t + 1);
;       const char* a2 = last ? nA + G_KT(0) : cA + G_KT(t + 2); const char* b2 = last ? nB + G_KT(0) : cB + G_KT(t + 2);
;       const char* a3 = last ? nA + G_KT(1) : cA + G_KT(t + 3); const char* b3 = last ? nB + G_KT(1) : cB + G_KT(t + 3);
;       G_LDB(B0, 0, 0); G_SCHED; G_LDA(At, 0, 0); G_STAGE(G_SA(1, 1), a1 + hstepA, voffA);
;       G_WAIT_L(8); G_BAR; G_WAIT_L(0); G_MMA(0, 0, At, B0); G_BAR; G_SCHED;
;       G_LDB(B1, 0, 1); G_STAGE(G_SB(0, 0), b2, voffB);
;       G_BAR; G_WAIT_L(0); G_MMA(0, 1, At, B1); G_BAR;
;       G_LDA(At, 0, 1); G_STAGE(G_SA(0, 0), a2, voffA);
;       G_BAR; G_WAIT_L(0); G_MMA(1, 0, At, B0); G_BAR; G_SCHED;
.LBB0_42:
	s_add_i32 s1, s57, 0xffffff80
	s_and_b32 s0, s44, 0xf80
	s_and_b32 s1, s1, 0xf00
	s_add_u32 s2, s70, s1
	s_addc_u32 s72, s71, 0
	s_add_u32 s1, s68, s1
	s_addc_u32 s73, s69, 0
	s_and_b32 s74, s57, 0xf80
	s_add_u32 s80, s70, s74
	s_addc_u32 s75, s71, 0
	s_add_u32 s54, s68, s74
	s_addc_u32 s55, s69, 0
	s_cmp_eq_u32 s7, 28
	s_cselect_b32 s77, vcc_lo, s72
	s_cselect_b32 s76, s47, s2
	s_cselect_b32 s79, s33, s73
	s_cselect_b32 s78, vcc_hi, s1
	s_cselect_b32 s75, s4, s75
	s_cselect_b32 s74, s97, s80
	s_cselect_b32 s73, s6, s55
	s_cselect_b32 s72, s5, s54
	s_add_i32 s2, s84, 0x100
	v_add_u32_e32 v140, s2, v162
	ds_read_b128 v[128:131], v140
	ds_read_b128 v[132:135], v140 offset:1024
	ds_read_b128 v[136:139], v140 offset:2048
	ds_read_b128 v[140:143], v140 offset:3072
	s_add_u32 s0, s21, s0
	s_addc_u32 s1, s23, 0
	v_lshl_add_u64 v[158:159], s[0:1], 0, v[148:149]
	s_add_i32 m0, s25, 0xc000
	ds_read_b128 v[154:157], v163
	ds_read_b128 v[164:167], v163 offset:1024
	ds_read_b128 v[168:171], v163 offset:2048
	ds_read_b128 v[172:175], v163 offset:3072
	ds_read_b128 v[176:179], v163 offset:4096
	ds_read_b128 v[180:183], v163 offset:5120
	ds_read_b128 v[184:187], v163 offset:6144
	ds_read_b128 v[188:191], v163 offset:7168
	global_load_lds_dwordx4 v[158:159], off
	v_lshl_add_u64 v[158:159], s[0:1], 0, v[150:151]
	s_add_i32 m0, s25, 0xe000
	s_nop 0
	global_load_lds_dwordx4 v[158:159], off
	s_waitcnt lgkmcnt(8)
	s_barrier
	s_waitcnt lgkmcnt(0)
	s_waitcnt lgkmcnt(0)
	v_mfma_f32_16x16x32_bf16 v[124:127], v[128:131], v[154:157], v[124:127]
	v_mfma_f32_16x16x32_bf16 v[120:123], v[136:139], v[154:157], v[120:123]
	v_mfma_f32_16x16x32_bf16 v[108:111], v[128:131], v[168:171], v[108:111]
	v_mfma_f32_16x16x32_bf16 v[104:107], v[136:139], v[168:171], v[104:107]
	v_mfma_f32_16x16x32_bf16 v[92:95], v[128:131], v[176:179], v[92:95]
	v_mfma_f32_16x16x32_bf16 v[88:91], v[136:139], v[176:179], v[88:91]
	v_mfma_f32_16x16x32_bf16 v[76:79], v[128:131], v[184:187], v[76:79]
	v_mfma_f32_16x16x32_bf16 v[72:75], v[136:139], v[184:187], v[72:75]
	v_mfma_f32_16x16x32_bf16 v[124:127], v[132:135], v[164:167], v[124:127]
	v_mfma_f32_16x16x32_bf16 v[120:123], v[140:143], v[164:167], v[120:123]
	v_mfma_f32_16x16x32_bf16 v[108:111], v[132:135], v[172:175], v[108:111]
	v_mfma_f32_16x16x32_bf16 v[104:107], v[140:143], v[172:175], v[104:107]
	v_mfma_f32_16x16x32_bf16 v[92:95], v[132:135], v[180:183], v[92:95]
	v_mfma_f32_16x16x32_bf16 v[88:91], v[140:143], v[180:183], v[88:91]
	v_mfma_f32_16x16x32_bf16 v[76:79], v[132:135], v[188:191], v[76:79]
	v_mfma_f32_16x16x32_bf16 v[72:75], v[140:143], v[188:191], v[72:75]
	s_barrier
	s_add_i32 s54, s85, 0x100
	v_add_u32_e32 v158, s54, v162
	s_add_i32 s0, s2, s14
	ds_read_b128 v[192:195], v158
	ds_read_b128 v[196:199], v158 offset:1024
	ds_read_b128 v[200:203], v158 offset:2048
	ds_read_b128 v[204:207], v158 offset:3072
	v_lshl_add_u64 v[158:159], s[78:79], 0, v[146:147]
	s_mov_b32 m0, s0
	s_nop 0
	global_load_lds_dwordx4 v[158:159], off
	v_lshl_add_u64 v[158:159], s[78:79], 0, v[152:153]
	s_add_i32 m0, s0, 0x2000
	s_nop 0
	global_load_lds_dwordx4 v[158:159], off
	s_barrier
	s_waitcnt lgkmcnt(0)
	s_waitcnt lgkmcnt(0)
	v_mfma_f32_16x16x32_bf16 v[116:119], v[192:195], v[154:157], v[116:119]
	v_mfma_f32_16x16x32_bf16 v[112:115], v[200:203], v[154:157], v[112:115]
	v_mfma_f32_16x16x32_bf16 v[100:103], v[192:195], v[168:171], v[100:103]
	v_mfma_f32_16x16x32_bf16 v[96:99], v[200:203], v[168:171], v[96:99]
	v_mfma_f32_16x16x32_bf16 v[84:87], v[192:195], v[176:179], v[84:87]
	v_mfma_f32_16x16x32_bf16 v[80:83], v[200:203], v[176:179], v[80:83]
	v_mfma_f32_16x16x32_bf16 v[68:71], v[192:195], v[184:187], v[68:71]
	v_mfma_f32_16x16x32_bf16 v[64:67], v[200:203], v[184:187], v[64:67]
	v_mfma_f32_16x16x32_bf16 v[116:119], v[196:199], v[164:167], v[116:119]
	v_mfma_f32_16x16x32_bf16 v[112:115], v[204:207], v[164:167], v[112:115]
	v_mfma_f32_16x16x32_bf16 v[100:103], v[196:199], v[172:175], v[100:103]
	v_mfma_f32_16x16x32_bf16 v[96:99], v[204:207], v[172:175], v[96:99]
	v_mfma_f32_16x16x32_bf16 v[84:87], v[196:199], v[180:183], v[84:87]
	v_mfma_f32_16x16x32_bf16 v[80:83], v[204:207], v[180:183], v[80:83]
	v_mfma_f32_16x16x32_bf16 v[68:71], v[196:199], v[188:191], v[68:71]
	v_mfma_f32_16x16x32_bf16 v[64:67], v[204:207], v[188:191], v[64:67]
	s_mov_b32 m0, s25
	v_lshl_add_u64 v[158:159], s[76:77], 0, v[148:149]
	s_barrier
	ds_read_b128 v[154:157], v163 offset:16384
	ds_read_b128 v[164:167], v163 offset:17408
	ds_read_b128 v[168:171], v163 offset:18432
	ds_read_b128 v[172:175], v163 offset:19456
	ds_read_b128 v[176:179], v163 offset:20480
	ds_read_b128 v[180:183], v163 offset:21504
	ds_read_b128 v[184:187], v163 offset:22528
	ds_read_b128 v[188:191], v163 offset:23552
	global_load_lds_dwordx4 v[158:159], off
	v_lshl_add_u64 v[158:159], s[76:77], 0, v[150:151]
	s_mov_b32 m0, s36
	s_nop 0
	global_load_lds_dwordx4 v[158:159], off
	s_barrier
	s_waitcnt lgkmcnt(0)
	s_waitcnt lgkmcnt(0)
	v_mfma_f32_16x16x32_bf16 v[60:63], v[128:131], v[154:157], v[60:63]
	v_mfma_f32_16x16x32_bf16 v[56:59], v[136:139], v[154:157], v[56:59]
	v_mfma_f32_16x16x32_bf16 v[44:47], v[128:131], v[168:171], v[44:47]
	v_mfma_f32_16x16x32_bf16 v[40:43], v[136:139], v[168:171], v[40:43]
	v_mfma_f32_16x16x32_bf16 v[28:31], v[128:131], v[176:179], v[28:31]
	v_mfma_f32_16x16x32_bf16 v[24:27], v[136:139], v[176:179], v[24:27]
	v_mfma_f32_16x16x32_bf16 v[20:23], v[128:131], v[184:187], v[20:23]
	v_mfma_f32_16x16x32_bf16 v[12:15], v[136:139], v[184:187], v[12:15]
	v_mfma_f32_16x16x32_bf16 v[60:63], v[132:135], v[164:167], v[60:63]
	v_mfma_f32_16x16x32_bf16 v[56:59], v[140:143], v[164:167], v[56:59]
	v_mfma_f32_16x16x32_bf16 v[44:47], v[132:135], v[172:175], v[44:47]
	v_mfma_f32_16x16x32_bf16 v[40:43], v[140:143], v[172:175], v[40:43]
	v_mfma_f32_16x16x32_bf16 v[28:31], v[132:135], v[180:183], v[28:31]
	v_mfma_f32_16x16x32_bf16 v[24:27], v[140:143], v[180:183], v[24:27]
	v_mfma_f32_16x16x32_bf16 v[20:23], v[132:135], v[188:191], v[20:23]
	v_mfma_f32_16x16x32_bf16 v[12:15], v[140:143], v[188:191], v[12:15]
	s_barrier
; #define G_STAGE(bufoff, gbase, voff) do { _Pragma("unroll") for (int _i = 0; _i < 2; ++_i) \
;         __builtin_amdgcn_global_load_lds((const unsigned*)((const char*)(gbase) + (voff)[_i]), (LAS unsigned*)(lds + (bufoff) + ldsw + _i * 8192), 16, 0, 0); } while (0)
; #define G_LDA(dst, b, h) do { _Pragma("unroll") for (int m = 0; m < 4; ++m) _Pragma("unroll") for (int k = 0; k < 2; ++k) dst[m][k] = *(const LAS bf16x8*)(lds + G_SA(b, h) + aoff + m * 2048 + k * 1024); } while (0)
; #define G_LDB(dst, b, h) do { _Pragma("unroll") for (int n = 0; n < 2; ++n) _Pragma("unroll") for (int k = 0; k < 2; ++k) dst[n][k] = *(const LAS bf16x8*)(lds + G_SB(b, h) + boff + n * 2048 + k * 1024); } while (0)
; #define G_MMA(ai, bj, At, Bt) do { __builtin_amdgcn_s_setprio(1); _Pragma("unroll") for (int m = 0; m < 4; ++m) _Pragma("unroll") for (int n = 0; n < 2; ++n) _Pragma("unroll") for (int k = 0; k < 2; ++k) \
;         acc[ai][bj][m][n] = __builtin_amdgcn_mfma_f32_16x16x32_bf16(Bt[n][k], At[m][k], acc[ai][bj][m][n], 0, 0, 0); __builtin_amdgcn_s_setprio(0); } while (0)
; #define G_WAIT_V(n) asm volatile("s_waitcnt vmcnt(" #n ")" ::: "memory")
; #define G_WAIT_L(n) asm volatile("s_waitcnt lgkmcnt(" #n ")" ::: "memory")
; #define G_BAR __builtin_amdgcn_s_barrier()
; #define G_SCHED __builtin_amdgcn_sched_barrier(0)
; template <class J>
; DI void gemm_phase(LAS unsigned char* lds, const J& job) {
;     ...
;       G_STAGE(G_SB(0, 1), b2 + hstepB, voffB);
;       G_WAIT_V(6); G_BAR; G_MMA(1, 1, At, B1); G_BAR;
;       G_LDB(B0, 1, 0); G_SCHED; G_LDA(At, 1, 0); G_STAGE(G_SA(0, 1), a2 + hstepA, voffA);
;       G_WAIT_L(8); G_BAR; G_WAIT_L(0); G_MMA(0, 0, At, B0); G_BAR; G_SCHED;
;       G_LDB(B1, 1, 1); G_STAGE(G_SB(1, 0), b3, voffB);
;       G_BAR; G_WAIT_L(0); G_MMA(0, 1, At, B1); G_BAR;
	s_add_u32 s0, s78, 0x80000
	s_addc_u32 s1, s79, 0
	s_add_i32 s2, s54, s14
	v_lshl_add_u64 v[128:129], s[0:1], 0, v[146:147]
	s_mov_b32 m0, s2
	s_nop 0
	global_load_lds_dwordx4 v[128:129], off
	v_lshl_add_u64 v[128:129], s[0:1], 0, v[152:153]
	s_add_i32 m0, s2, 0x2000
	s_nop 0
	global_load_lds_dwordx4 v[128:129], off
	s_waitcnt vmcnt(6)
	s_barrier
	v_mfma_f32_16x16x32_bf16 v[52:55], v[192:195], v[154:157], v[52:55]
	v_mfma_f32_16x16x32_bf16 v[48:51], v[200:203], v[154:157], v[48:51]
	v_mfma_f32_16x16x32_bf16 v[36:39], v[192:195], v[168:171], v[36:39]
	v_mfma_f32_16x16x32_bf16 v[32:35], v[200:203], v[168:171], v[32:35]
	v_mfma_f32_16x16x32_bf16 v[16:19], v[192:195], v[176:179], v[16:19]
	v_mfma_f32_16x16x32_bf16 v[8:11], v[200:203], v[176:179], v[8:11]
	v_mfma_f32_16x16x32_bf16 v[4:7], v[192:195], v[184:187], v[4:7]
	v_mfma_f32_16x16x32_bf16 v[0:3], v[200:203], v[184:187], v[0:3]
	v_mfma_f32_16x16x32_bf16 v[52:55], v[196:199], v[164:167], v[52:55]
	v_mfma_f32_16x16x32_bf16 v[48:51], v[204:207], v[164:167], v[48:51]
	v_mfma_f32_16x16x32_bf16 v[36:39], v[196:199], v[172:175], v[36:39]
	v_mfma_f32_16x16x32_bf16 v[32:35], v[204:207], v[172:175], v[32:35]
	v_mfma_f32_16x16x32_bf16 v[16:19], v[196:199], v[180:183], v[16:19]
	v_mfma_f32_16x16x32_bf16 v[8:11], v[204:207], v[180:183], v[8:11]
	v_mfma_f32_16x16x32_bf16 v[4:7], v[196:199], v[188:191], v[4:7]
	v_mfma_f32_16x16x32_bf16 v[0:3], v[204:207], v[188:191], v[0:3]
	s_add_i32 s2, s88, 0x100
	v_add_u32_e32 v140, s2, v162
	s_barrier
	ds_read_b128 v[128:131], v140
	ds_read_b128 v[132:135], v140 offset:1024
	ds_read_b128 v[136:139], v140 offset:2048
	ds_read_b128 v[140:143], v140 offset:3072
	s_add_u32 s0, s76, 0x80000
	s_addc_u32 s1, s77, 0
	s_mov_b32 m0, s37
	v_lshl_add_u64 v[158:159], s[0:1], 0, v[148:149]
	ds_read_b128 v[154:157], v163 offset:32768
	ds_read_b128 v[164:167], v163 offset:33792
	ds_read_b128 v[168:171], v163 offset:34816
	ds_read_b128 v[172:175], v163 offset:35840
	ds_read_b128 v[176:179], v163 offset:36864
	ds_read_b128 v[180:183], v163 offset:37888
	ds_read_b128 v[184:187], v163 offset:38912
	ds_read_b128 v[188:191], v163 offset:39936
	global_load_lds_dwordx4 v[158:159], off
	v_lshl_add_u64 v[158:159], s[0:1], 0, v[150:151]
	s_mov_b32 m0, s38
	s_nop 0
	global_load_lds_dwordx4 v[158:159], off
	s_waitcnt lgkmcnt(8)
	s_barrier
	s_waitcnt lgkmcnt(0)
	s_waitcnt lgkmcnt(0)
	v_mfma_f32_16x16x32_bf16 v[124:127], v[128:131], v[154:157], v[124:127]
	v_mfma_f32_16x16x32_bf16 v[120:123], v[136:139], v[154:157], v[120:123]
	v_mfma_f32_16x16x32_bf16 v[108:111], v[128:131], v[168:171], v[108:111]
	v_mfma_f32_16x16x32_bf16 v[104:107], v[136:139], v[168:171], v[104:107]
	v_mfma_f32_16x16x32_bf16 v[92:95], v[128:131], v[176:179], v[92:95]
	v_mfma_f32_16x16x32_bf16 v[88:91], v[136:139], v[176:179], v[88:91]
	v_mfma_f32_16x16x32_bf16 v[76:79], v[128:131], v[184:187], v[76:79]
	v_mfma_f32_16x16x32_bf16 v[72:75], v[136:139], v[184:187], v[72:75]
	v_mfma_f32_16x16x32_bf16 v[124:127], v[132:135], v[164:167], v[124:127]
	v_mfma_f32_16x16x32_bf16 v[120:123], v[140:143], v[164:167], v[120:123]
	v_mfma_f32_16x16x32_bf16 v[108:111], v[132:135], v[172:175], v[108:111]
	v_mfma_f32_16x16x32_bf16 v[104:107], v[140:143], v[172:175], v[104:107]
	v_mfma_f32_16x16x32_bf16 v[92:95], v[132:135], v[180:183], v[92:95]
	v_mfma_f32_16x16x32_bf16 v[88:91], v[140:143], v[180:183], v[88:91]
	v_mfma_f32_16x16x32_bf16 v[76:79], v[132:135], v[188:191], v[76:79]
	v_mfma_f32_16x16x32_bf16 v[72:75], v[140:143], v[188:191], v[72:75]
	s_barrier
	s_add_i32 s54, s89, 0x100
	v_add_u32_e32 v158, s54, v162
	s_add_i32 s0, s2, s14
	ds_read_b128 v[192:195], v158
	ds_read_b128 v[196:199], v158 offset:1024
	ds_read_b128 v[200:203], v158 offset:2048
	ds_read_b128 v[204:207], v158 offset:3072
	v_lshl_add_u64 v[158:159], s[72:73], 0, v[146:147]
	s_mov_b32 m0, s0
	s_nop 0
	global_load_lds_dwordx4 v[158:159], off
	v_lshl_add_u64 v[158:159], s[72:73], 0, v[152:153]
	s_add_i32 m0, s0, 0x2000
	s_nop 0
	global_load_lds_dwordx4 v[158:159], off
	s_barrier
	s_waitcnt lgkmcnt(0)
	s_waitcnt lgkmcnt(0)
	v_mfma_f32_16x16x32_bf16 v[116:119], v[192:195], v[154:157], v[116:119]
	v_mfma_f32_16x16x32_bf16 v[112:115], v[200:203], v[154:157], v[112:115]
	v_mfma_f32_16x16x32_bf16 v[100:103], v[192:195], v[168:171], v[100:103]
	v_mfma_f32_16x16x32_bf16 v[96:99], v[200:203], v[168:171], v[96:99]
	v_mfma_f32_16x16x32_bf16 v[84:87], v[192:195], v[176:179], v[84:87]
	v_mfma_f32_16x16x32_bf16 v[80:83], v[200:203], v[176:179], v[80:83]
	v_mfma_f32_16x16x32_bf16 v[68:71], v[192:195], v[184:187], v[68:71]
	v_mfma_f32_16x16x32_bf16 v[64:67], v[200:203], v[184:187], v[64:67]
	v_mfma_f32_16x16x32_bf16 v[116:119], v[196:199], v[164:167], v[116:119]
	v_mfma_f32_16x16x32_bf16 v[112:115], v[204:207], v[164:167], v[112:115]
	v_mfma_f32_16x16x32_bf16 v[100:103], v[196:199], v[172:175], v[100:103]
	v_mfma_f32_16x16x32_bf16 v[96:99], v[204:207], v[172:175], v[96:99]
	v_mfma_f32_16x16x32_bf16 v[84:87], v[196:199], v[180:183], v[84:87]
	v_mfma_f32_16x16x32_bf16 v[80:83], v[204:207], v[180:183], v[80:83]
	v_mfma_f32_16x16x32_bf16 v[68:71], v[196:199], v[188:191], v[68:71]
	v_mfma_f32_16x16x32_bf16 v[64:67], v[204:207], v[188:191], v[64:67]
	s_mov_b32 m0, s87
	v_lshl_add_u64 v[158:159], s[74:75], 0, v[148:149]
	s_barrier
; #define G_STAGE(bufoff, gbase, voff) do { _Pragma("unroll") for (int _i = 0; _i < 2; ++_i) \
;         __builtin_amdgcn_global_load_lds((const unsigned*)((const char*)(gbase) + (voff)[_i]), (LAS unsigned*)(lds + (bufoff) + ldsw + _i * 8192), 16, 0, 0); } while (0)
; #define G_LDA(dst, b, h) do { _Pragma("unroll") for (int m = 0; m < 4; ++m) _Pragma("unroll") for (int k = 0; k < 2; ++k) dst[m][k] = *(const LAS bf16x8*)(lds + G_SA(b, h) + aoff + m * 2048 + k * 1024); } while (0)
; #define G_MMA(ai, bj, At, Bt) do { __builtin_amdgcn_s_setprio(1); _Pragma("unroll") for (int m = 0; m < 4; ++m) _Pragma("unroll") for (int n = 0; n < 2; ++n) _Pragma("unroll") for (int k = 0; k < 2; ++k) \
;         acc[ai][bj][m][n] = __builtin_amdgcn_mfma_f32_16x16x32_bf16(Bt[n][k], At[m][k], acc[ai][bj][m][n], 0, 0, 0); __builtin_amdgcn_s_setprio(0); } while (0)
; #define G_WAIT_V(n) asm volatile("s_waitcnt vmcnt(" #n ")" ::: "memory")
; #define G_WAIT_L(n) asm volatile("s_waitcnt lgkmcnt(" #n ")" ::: "memory")
; #define G_BAR __builtin_amdgcn_s_barrier()
; #define G_SCHED __builtin_amdgcn_sched_barrier(0)
; template <class J>
; DI void gemm_phase(LAS unsigned char* lds, const J& job) {
;     ...
;       G_LDA(At, 1, 1); G_STAGE(G_SA(1, 0), a3, voffA);
;       G_BAR; G_WAIT_L(0); G_MMA(1, 0, At, B0); G_BAR; G_SCHED;
;       G_STAGE(G_SB(1, 1), b3 + hstepB, voffB);
;       G_WAIT_V(6); G_BAR; G_MMA(1, 1, At, B1); G_BAR;
;   DI void epi(const Acc& acc, const Unit& u, int wr, int wc, int fr, int fq) const {
;     ...
;     for (int ai = 0; ai < 2; ++ai) {
;       f32x4 res[4][2][2];
; #pragma unroll
;       for (int m = 0; m < 4; ++m) {
;         const int row = u.pm * 256 + ai * HALF + wr * 64 + m * 16 + fr;
;         const float* src = (l == 0) ? xp + (size_t)row * DM : out + (size_t)row * DM;
; #pragma unroll
;         for (int bj = 0; bj < 2; ++bj) { const int col = u.pn * 256 + bj * HALF + wc * 32 + 8 * fq; res[m][bj][0] = *(const f32x4*)(src + col); res[m][bj][1] = *(const f32x4*)(src + col + 4); }
;       }
	ds_read_b128 v[154:157], v163 offset:49152
	ds_read_b128 v[164:167], v163 offset:50176
	ds_read_b128 v[168:171], v163 offset:51200
	ds_read_b128 v[172:175], v163 offset:52224
	ds_read_b128 v[176:179], v163 offset:53248
	ds_read_b128 v[180:183], v163 offset:54272
	ds_read_b128 v[184:187], v163 offset:55296
	ds_read_b128 v[188:191], v163 offset:56320
	global_load_lds_dwordx4 v[158:159], off
	v_lshl_add_u64 v[158:159], s[74:75], 0, v[150:151]
	s_mov_b32 m0, s94
	s_nop 0
	global_load_lds_dwordx4 v[158:159], off
	s_barrier
	s_waitcnt lgkmcnt(0)
	s_waitcnt lgkmcnt(0)
	v_mfma_f32_16x16x32_bf16 v[60:63], v[128:131], v[154:157], v[60:63]
	v_mfma_f32_16x16x32_bf16 v[56:59], v[136:139], v[154:157], v[56:59]
	v_mfma_f32_16x16x32_bf16 v[44:47], v[128:131], v[168:171], v[44:47]
	v_mfma_f32_16x16x32_bf16 v[40:43], v[136:139], v[168:171], v[40:43]
	v_mfma_f32_16x16x32_bf16 v[28:31], v[128:131], v[176:179], v[28:31]
	v_mfma_f32_16x16x32_bf16 v[24:27], v[136:139], v[176:179], v[24:27]
	v_mfma_f32_16x16x32_bf16 v[20:23], v[128:131], v[184:187], v[20:23]
	v_mfma_f32_16x16x32_bf16 v[12:15], v[136:139], v[184:187], v[12:15]
	v_mfma_f32_16x16x32_bf16 v[60:63], v[132:135], v[164:167], v[60:63]
	v_mfma_f32_16x16x32_bf16 v[56:59], v[140:143], v[164:167], v[56:59]
	v_mfma_f32_16x16x32_bf16 v[44:47], v[132:135], v[172:175], v[44:47]
	v_mfma_f32_16x16x32_bf16 v[40:43], v[140:143], v[172:175], v[40:43]
	v_mfma_f32_16x16x32_bf16 v[28:31], v[132:135], v[180:183], v[28:31]
	v_mfma_f32_16x16x32_bf16 v[24:27], v[140:143], v[180:183], v[24:27]
	v_mfma_f32_16x16x32_bf16 v[20:23], v[132:135], v[188:191], v[20:23]
	v_mfma_f32_16x16x32_bf16 v[12:15], v[140:143], v[188:191], v[12:15]
	s_barrier
	s_add_u32 s0, s72, 0x80000
	s_addc_u32 s1, s73, 0
	s_add_i32 s2, s54, s14
	v_lshl_add_u64 v[128:129], s[0:1], 0, v[146:147]
	s_mov_b32 m0, s2
	s_nop 0
	global_load_lds_dwordx4 v[128:129], off
	v_lshl_add_u64 v[128:129], s[0:1], 0, v[152:153]
	s_add_i32 m0, s2, 0x2000
	s_nop 0
	global_load_lds_dwordx4 v[128:129], off
	s_waitcnt vmcnt(6)
	s_barrier
	v_mfma_f32_16x16x32_bf16 v[52:55], v[192:195], v[154:157], v[52:55]
	v_mfma_f32_16x16x32_bf16 v[48:51], v[200:203], v[154:157], v[48:51]
	v_mfma_f32_16x16x32_bf16 v[36:39], v[192:195], v[168:171], v[36:39]
	v_mfma_f32_16x16x32_bf16 v[32:35], v[200:203], v[168:171], v[32:35]
	v_mfma_f32_16x16x32_bf16 v[16:19], v[192:195], v[176:179], v[16:19]
	v_mfma_f32_16x16x32_bf16 v[8:11], v[200:203], v[176:179], v[8:11]
	v_mfma_f32_16x16x32_bf16 v[4:7], v[192:195], v[184:187], v[4:7]
	v_mfma_f32_16x16x32_bf16 v[0:3], v[200:203], v[184:187], v[0:3]
	v_mfma_f32_16x16x32_bf16 v[52:55], v[196:199], v[164:167], v[52:55]
	v_mfma_f32_16x16x32_bf16 v[48:51], v[204:207], v[164:167], v[48:51]
	v_mfma_f32_16x16x32_bf16 v[36:39], v[196:199], v[172:175], v[36:39]
	v_mfma_f32_16x16x32_bf16 v[32:35], v[204:207], v[172:175], v[32:35]
	v_mfma_f32_16x16x32_bf16 v[16:19], v[196:199], v[180:183], v[16:19]
	v_mfma_f32_16x16x32_bf16 v[8:11], v[204:207], v[180:183], v[8:11]
	v_mfma_f32_16x16x32_bf16 v[4:7], v[196:199], v[188:191], v[4:7]
	v_mfma_f32_16x16x32_bf16 v[0:3], v[204:207], v[188:191], v[0:3]
	s_add_i32 s7, s7, 2
	s_addk_i32 s57, 0x100
	s_addk_i32 s44, 0x100
	s_cmp_gt_u32 s7, 29
	s_barrier
	s_cbranch_scc0 .LBB0_42
	s_lshl_b32 s0, s66, 8
	v_mov_b32_e32 v128, v161
	v_mov_b32_e32 v129, v160
	s_add_i32 s0, s0, s67
	s_and_b64 vcc, exec, s[18:19]
	v_add_u32_e32 v156, s0, v129
	s_lshl_b32 s0, s46, 8
	s_or_b32 s0, s0, s83
	v_lshl_add_u32 v128, v128, 3, s0
	v_ashrrev_i32_e32 v157, 31, v156
	v_ashrrev_i32_e32 v129, 31, v128
	v_lshlrev_b64 v[212:213], 13, v[156:157]
	v_lshl_add_u64 v[130:131], s[8:9], 0, v[212:213]
	v_lshlrev_b64 v[154:155], 2, v[128:129]
	v_lshl_add_u64 v[128:129], v[130:131], 0, v[154:155]
	global_load_dwordx4 v[164:167], v[128:129], off offset:16
	global_load_dwordx4 v[168:171], v[128:129], off
	global_load_dwordx4 v[172:175], v[128:129], off offset:528
	global_load_dwordx4 v[176:179], v[128:129], off offset:512
	v_add_u32_e32 v128, 16, v156
	v_ashrrev_i32_e32 v129, 31, v128
	v_lshlrev_b64 v[214:215], 13, v[128:129]
	v_lshl_add_u64 v[128:129], s[8:9], 0, v[214:215]
	v_lshl_add_u64 v[128:129], v[128:129], 0, v[154:155]
	global_load_dwordx4 v[180:183], v[128:129], off offset:16
	global_load_dwordx4 v[184:187], v[128:129], off
	global_load_dwordx4 v[188:191], v[128:129], off offset:528
	global_load_dwordx4 v[192:195], v[128:129], off offset:512
	v_add_u32_e32 v128, 32, v156
	v_ashrrev_i32_e32 v129, 31, v128
	v_lshlrev_b64 v[216:217], 13, v[128:129]
	v_lshl_add_u64 v[128:129], s[8:9], 0, v[216:217]
	v_lshl_add_u64 v[128:129], v[128:129], 0, v[154:155]
	global_load_dwordx4 v[196:199], v[128:129], off offset:16
	global_load_dwordx4 v[200:203], v[128:129], off
	global_load_dwordx4 v[204:207], v[128:129], off offset:528
	global_load_dwordx4 v[208:211], v[128:129], off offset:512
	v_add_u32_e32 v128, 48, v156
	v_ashrrev_i32_e32 v129, 31, v128
	v_lshlrev_b64 v[158:159], 13, v[128:129]
	v_lshl_add_u64 v[128:129], s[8:9], 0, v[158:159]
	v_lshl_add_u64 v[136:137], v[128:129], 0, v[154:155]
	global_load_dwordx4 v[132:135], v[136:137], off offset:16
	global_load_dwordx4 v[140:143], v[136:137], off
	global_load_dwordx4 v[128:131], v[136:137], off offset:528
	s_nop 0
	global_load_dwordx4 v[136:139], v[136:137], off offset:512
	v_lshl_add_u64 v[212:213], s[16:17], 0, v[212:213]
	s_mov_b32 s46, s22
	s_mov_b32 s66, s20
	s_mov_b64 s[68:69], s[64:65]
	s_mov_b64 s[70:71], s[62:63]
	s_movk_i32 s54, 0x4000
	s_movk_i32 s55, 0x6000
	v_readlane_b32 s0, v255, 23
	s_cmpk_gt_u32 s0, 0xff
	s_cbranch_scc1 .Lds_out_x
	s_barrier

; #define G_WAIT_V(n) asm volatile("s_waitcnt vmcnt(" #n ")" ::: "memory")
; #define G_BAR __builtin_amdgcn_s_barrier()
; template <class J>
; DI void gemm_phase(LAS unsigned char* lds, const J& job) {
;     ...
;   G_WAIT_V(0);
;   if (wr == 0) G_BAR;
;   G_BAR;
.Lds_out_done:
	s_setprio 0
	s_waitcnt vmcnt(0)
	v_readlane_b32 s0, v255, 23
	s_cmpk_gt_u32 s0, 0xff
	s_cbranch_scc1 .LBB0_46

; DI int my_tid() { int t = threadIdx.x; asm volatile("" : "+v"(t)); return t; }
; DI int my_block() { int b = blockIdx.x; asm volatile("" : "+s"(b)); return b; }
; #define G_STAGE(bufoff, gbase, voff) do { _Pragma("unroll") for (int _i = 0; _i < 2; ++_i) \
;         __builtin_amdgcn_global_load_lds((const unsigned*)((const char*)(gbase) + (voff)[_i]), (LAS unsigned*)(lds + (bufoff) + ldsw + _i * 8192), 16, 0, 0); } while (0)
; template <class J>
; DI void gemm_phase(LAS unsigned char* lds, const J& job) {
;   const int tid = my_tid(), wid = __builtin_amdgcn_readfirstlane(tid >> 6), lane = tid & 63, wr = wid >> 2, wc = wid & 3, fr = lane & 15, fq = lane >> 4;
;   const int nt = job.nt;
;   unsigned voffA[2], voffB[2];
; #pragma unroll
;   for (int i = 0; i < 2; ++i) { int R, C; stage_rc(tid * 16 + i * 8192, R, C); const int Rb = job.brow_of(R);
;     voffA[i] = (unsigned)(R * job.lda + C) * 2u; voffB[i] = (unsigned)(Rb * job.ldb + C) * 2u; }
;   const size_t kstep = (size_t)(BK * 2);
;   const size_t hstepA = (size_t)HALF * job.lda * 2, hstepB = (size_t)job.bhalf_rows() * job.ldb * 2;
;   const unsigned ldsw = (unsigned)wid * 1024u;
;   const int aoff = lds_byte(wr * 64 + fr, fq * 8), boff = lds_byte(wc * 32 + fr, fq * 8);
;     ...
;   Unit cur, nxt; int ui = 0;
;   if (!job.next(0, cur)) return;
;   f32x4 acc[2][2][4][2];
; #pragma unroll
;   for (int a = 0; a < 2; ++a)
; #pragma unroll
;     for (int b = 0; b < 2; ++b)
; #pragma unroll
;       for (int m = 0; m < 4; ++m)
; #pragma unroll
;         for (int n = 0; n < 2; ++n) acc[a][b][m][n] = (f32x4){0.f, 0.f, 0.f, 0.f};
;   bf16x8 At[4][2], B0[2][2], B1[2][2];
;   const char* cA = job.aptr(cur); const char* cB = job.bptr(cur);
;   const int koff = (my_block() & 7) * (nt >> 3), kmask = nt - 1;
;     ...
;   G_STAGE(G_SB(0, 0), cB + G_KT(0), voffB); G_STAGE(G_SA(0, 0), cA + G_KT(0), voffA); G_STAGE(G_SB(0, 1), cB + hstepB + G_KT(0), voffB); G_STAGE(G_SA(0, 1), cA + hstepA + G_KT(0), voffA);
;   if (wr == 1) G_BAR;
;   DI int brow_of(int R) const { return ((R >> 4) & 1) * 2048 + 16 * (R >> 5) + (R & 15); }
;     u.pn = ((((u.pn >> 2) + (c & 7)) & 7) << 2) + (u.pn & 3);
;     return true; }
;   DI const char* aptr(const Unit& u) const { return (const char*)(h + (size_t)u.pm * 256 * DM); }
;   DI const char* bptr(const Unit& u) const { return (const char*)(wgT + (size_t)u.pn * 64 * DM); }
.LBB0_64:
	v_bfe_i32 v3, v0, 27, 1
	v_lshlrev_b32_e32 v1, 4, v0
	v_lshrrev_b32_e32 v3, 22, v3
	v_add_u32_e32 v3, v1, v3
	v_and_b32_e32 v3, 0xfffffc00, v3
	v_ashrrev_i32_e32 v2, 31, v0
	v_sub_u32_e32 v3, v1, v3
	v_lshrrev_b32_e32 v2, 26, v2
	s_waitcnt vmcnt(0)
	v_lshrrev_b32_e32 v4, 4, v3
	v_add_u32_e32 v2, v0, v2
	v_bitop3_b32 v4, v4, v3, 32 bitop3:0x6c
	v_ashrrev_i32_e32 v3, 31, v3
	s_ashr_i32 s0, s5, 3
	v_writelane_b32 v255, s87, 22
	v_ashrrev_i32_e32 v2, 6, v2
	v_lshrrev_b32_e32 v3, 26, v3
	s_add_i32 s0, s7, s0
	s_ashr_i32 s4, s1, 6
	v_lshlrev_b32_e32 v5, 3, v2
	v_add_u32_e32 v3, v4, v3
	v_writelane_b32 v255, s1, 23
	s_ashr_i32 s6, s1, 8
	s_ashr_i32 s1, s0, 31
	v_and_b32_e32 v5, -16, v5
	v_ashrrev_i32_e32 v3, 6, v3
	s_lshr_b32 s1, s1, 24
	v_add_u32_e32 v5, v3, v5
	v_mul_i32_i24_e32 v6, 64, v3
	s_add_i32 s1, s0, s1
	v_sub_u32_e32 v4, v4, v6
	v_lshlrev_b32_e32 v6, 7, v5
	v_lshrrev_b32_e32 v7, 1, v5
	s_ashr_i32 s5, s1, 8
	s_and_b32 s1, s1, 0xffffff00
	v_lshlrev_b32_e32 v2, 5, v2
	v_ashrrev_i16_sdwa v4, v220, sext(v4) dst_sel:DWORD dst_unused:UNUSED_PAD src0_sel:DWORD src1_sel:BYTE_0
	v_and_b32_e32 v6, 0x800, v6
	v_and_b32_e32 v7, 0xffff0, v7
	s_sub_i32 s0, s0, s1
	v_and_b32_e32 v2, 32, v2
	v_bfe_i32 v4, v4, 0, 16
	v_add_u32_e32 v6, v6, v7
	s_sext_i32_i16 s1, s0
	v_and_or_b32 v3, v3, 15, v6
	v_add_lshl_u32 v2, v2, v4, 1
	v_add_u32_e32 v1, 0x2000, v1
	s_bfe_u32 s1, s1, 0x3001c
	v_lshl_add_u32 v148, v5, 12, v2
	v_lshl_add_u32 v146, v3, 12, v2
	v_ashrrev_i32_e32 v2, 31, v1
	s_add_i32 s1, s0, s1
	v_lshrrev_b32_e32 v2, 22, v2
	s_sext_i32_i16 s7, s1
	s_and_b32 s1, s1, 0xfff8
	v_add_u32_e32 v2, v1, v2
	s_sub_i32 s0, s0, s1
	v_ashrrev_i32_e32 v2, 10, v2
	s_lshl_b32 s5, s5, 3
	s_lshr_b32 s8, s7, 3
	s_sext_i32_i16 s0, s0
	s_lshl_b32 s79, s43, 2
	v_mul_i32_i24_e32 v3, 0x400, v2
	s_add_i32 s64, s5, s0
	s_add_i32 s0, s79, s8
	v_sub_u32_e32 v1, v1, v3
	s_and_b32 s0, s0, 28
	s_bfe_u32 s1, s7, 0x20003
	v_lshrrev_b32_e32 v3, 4, v1
	s_or_b32 s44, s0, s1
	s_ashr_i32 s65, s64, 31
	v_bitop3_b32 v1, v3, v1, 32 bitop3:0x6c
	s_lshl_b32 s78, s4, 10
	s_lshl_b64 s[8:9], s[64:65], 20
	s_lshl_b32 s0, s44, 18
	v_ashrrev_i32_e32 v4, 31, v1
	s_add_u32 s66, s16, s0
	s_mov_b32 s5, s2
	v_lshrrev_b32_e32 v4, 26, v4
	s_addc_u32 s67, s17, 0
	s_lshl_b32 s0, s5, 2
	v_lshlrev_b32_e32 v3, 3, v2
	v_add_u32_e32 v4, v1, v4
	s_and_b32 s0, s0, 28
	v_and_b32_e32 v3, -16, v3
	v_ashrrev_i32_e32 v5, 6, v4
	s_lshl_b32 s65, s0, 7
	v_add_u32_e32 v3, v5, v3
	v_and_b32_e32 v4, 0xc0, v4
	s_add_u32 s18, s66, s65
	v_sub_u32_e32 v1, v1, v4
	v_lshlrev_b32_e32 v4, 7, v3
	v_lshrrev_b32_e32 v6, 1, v3
	s_addc_u32 s19, s67, 0
	s_add_i32 s14, s78, 0x100
	v_lshlrev_b32_e32 v2, 5, v2
	v_ashrrev_i16_sdwa v1, v220, sext(v1) dst_sel:DWORD dst_unused:UNUSED_PAD src0_sel:DWORD src1_sel:BYTE_0
	v_and_b32_e32 v4, 0x800, v4
	v_and_b32_e32 v6, 0xffff0, v6
	s_add_i32 m0, s14, 0x10000
	v_and_b32_e32 v2, 32, v2
	v_bfe_i32 v1, v1, 0, 16
	v_add_u32_e32 v4, v4, v6
	global_load_lds_dwordx4 v146, s[18:19]
	s_add_i32 m0, s14, 0x12000
	v_and_or_b32 v4, v5, 15, v4
	v_add_lshl_u32 v1, v2, v1, 1
	s_add_u32 s68, s58, s8
	v_lshl_add_u32 v152, v4, 12, v1
	s_addc_u32 s69, s59, s9
	global_load_lds_dwordx4 v152, s[18:19]
	s_add_u32 s18, s68, s65
	s_addc_u32 s19, s69, 0
	s_add_i32 s15, s14, 0x2000
	s_add_u32 s7, s66, 0x1000000
	s_mov_b32 m0, s14
	s_addc_u32 s8, s67, 0
	v_lshl_add_u32 v150, v3, 12, v1
	global_load_lds_dwordx4 v148, s[18:19]
	s_mov_b32 m0, s15
	s_add_u32 s20, s7, s65
	global_load_lds_dwordx4 v150, s[18:19]
	s_addc_u32 s21, s8, 0
	s_add_i32 m0, s14, 0x14000
	v_mov_b32_e32 v245, 0x2000
	global_load_lds_dwordx4 v146, s[20:21]
	s_add_i32 m0, s14, 0x16000
	s_add_u32 s18, s18, 0x80000
	s_addc_u32 s19, s19, 0
	s_add_i32 s83, s14, 0x4000
	global_load_lds_dwordx4 v152, s[20:21]
	s_mov_b32 m0, s83
	s_add_i32 s36, s14, 0x6000
	global_load_lds_dwordx4 v148, s[18:19]
	s_mov_b32 m0, s36
	v_mov_b32_e32 v254, 1
	global_load_lds_dwordx4 v150, s[18:19]
	s_cmp_lg_u32 s6, 1
	s_cbranch_scc1 .LBB0_66
	s_barrier
	s_setprio 1

; #define G_STAGE(bufoff, gbase, voff) do { _Pragma("unroll") for (int _i = 0; _i < 2; ++_i) \
;         __builtin_amdgcn_global_load_lds((const unsigned*)((const char*)(gbase) + (voff)[_i]), (LAS unsigned*)(lds + (bufoff) + ldsw + _i * 8192), 16, 0, 0); } while (0)
; #define G_LDA(dst, b, h) do { _Pragma("unroll") for (int m = 0; m < 4; ++m) _Pragma("unroll") for (int k = 0; k < 2; ++k) dst[m][k] = *(const LAS bf16x8*)(lds + G_SA(b, h) + aoff + m * 2048 + k * 1024); } while (0)
; #define G_LDB(dst, b, h) do { _Pragma("unroll") for (int n = 0; n < 2; ++n) _Pragma("unroll") for (int k = 0; k < 2; ++k) dst[n][k] = *(const LAS bf16x8*)(lds + G_SB(b, h) + boff + n * 2048 + k * 1024); } while (0)
; #define G_MMA(ai, bj, At, Bt) do { __builtin_amdgcn_s_setprio(1); _Pragma("unroll") for (int m = 0; m < 4; ++m) _Pragma("unroll") for (int n = 0; n < 2; ++n) _Pragma("unroll") for (int k = 0; k < 2; ++k) \
;         acc[ai][bj][m][n] = __builtin_amdgcn_mfma_f32_16x16x32_bf16(Bt[n][k], At[m][k], acc[ai][bj][m][n], 0, 0, 0); __builtin_amdgcn_s_setprio(0); } while (0)
; #define G_WAIT_L(n) asm volatile("s_waitcnt lgkmcnt(" #n ")" ::: "memory")
; #define G_BAR __builtin_amdgcn_s_barrier()
; #define G_SCHED __builtin_amdgcn_sched_barrier(0)
;   DI const char* aptr(const Unit& u) const { return (const char*)(h + (size_t)u.pm * 256 * DM); }
; template <class J>
; DI void gemm_phase(LAS unsigned char* lds, const J& job) {
;     ...
;     const bool has_next = job.next(ui + 1, nxt);
;     const char* nA = has_next ? job.aptr(nxt) : cA; const char* nB = has_next ? job.bptr(nxt) : cB;
;     for (int t = 0; t < nt; t += 2) {
;       const bool last = (t == nt - 2);
;       const char* a1 = cA + G_KT(t + 1);
;       const char* a2 = last ? nA + G_KT(0) : cA + G_KT(t + 2); const char* b2 = last ? nB + G_KT(0) : cB + G_KT(t + 2);
;       const char* a3 = last ? nA + G_KT(1) : cA + G_KT(t + 3); const char* b3 = last ? nB + G_KT(1) : cB + G_KT(t + 3);
;       G_LDB(B0, 0, 0); G_SCHED; G_LDA(At, 0, 0); G_STAGE(G_SA(1, 1), a1 + hstepA, voffA);
;       G_WAIT_L(8); G_BAR; G_WAIT_L(0); G_MMA(0, 0, At, B0); G_BAR; G_SCHED;
;       G_LDB(B1, 0, 1); G_STAGE(G_SB(0, 0), b2, voffB);
;       G_BAR; G_WAIT_L(0); G_MMA(0, 1, At, B1); G_BAR;
;       G_LDA(At, 0, 1); G_STAGE(G_SA(0, 0), a2, voffA);
;       G_BAR; G_WAIT_L(0); G_MMA(1, 0, At, B0); G_BAR; G_SCHED;
.LBB0_74:
	s_add_i32 s1, s56, 0xffffff80
	s_and_b32 s0, s7, 0xf80
	s_and_b32 s1, s1, 0xf00
	s_add_u32 s57, s68, s1
	s_addc_u32 s70, s69, 0
	s_add_u32 s1, s66, s1
	s_addc_u32 s71, s67, 0
	s_and_b32 s72, s56, 0xf80
	s_add_u32 s80, s68, s72
	s_addc_u32 s73, s69, 0
	s_add_u32 s38, s66, s72
	s_addc_u32 s2, s67, 0
	s_cmp_eq_u32 s6, 28
	s_cselect_b32 s75, s46, s70
	s_cselect_b32 s74, s45, s57
	s_cselect_b32 s77, vcc_lo, s71
	s_cselect_b32 s76, s47, s1
	s_cselect_b32 s73, s97, s73
	s_cselect_b32 s72, s33, s80
	s_cselect_b32 s71, s5, s2
	s_cselect_b32 s70, vcc_hi, s38
	s_add_i32 s2, s84, 0x100
	v_add_u32_e32 v100, s2, v248
	ds_read_b128 v[84:87], v100
	ds_read_b128 v[88:91], v100 offset:1024
	ds_read_b128 v[96:99], v100 offset:2048
	ds_read_b128 v[100:103], v100 offset:3072
	s_add_u32 s0, s19, s0
	s_addc_u32 s1, s21, 0
	v_lshl_add_u64 v[186:187], s[0:1], 0, v[148:149]
	s_add_i32 m0, s14, 0xc000
	ds_read_b128 v[154:157], v249
	ds_read_b128 v[158:161], v249 offset:1024
	ds_read_b128 v[162:165], v249 offset:2048
	ds_read_b128 v[166:169], v249 offset:3072
	ds_read_b128 v[170:173], v249 offset:4096
	ds_read_b128 v[174:177], v249 offset:5120
	ds_read_b128 v[178:181], v249 offset:6144
	ds_read_b128 v[182:185], v249 offset:7168
	global_load_lds_dwordx4 v[186:187], off
	v_lshl_add_u64 v[186:187], s[0:1], 0, v[150:151]
	s_add_i32 m0, s14, 0xe000
	s_nop 0
	global_load_lds_dwordx4 v[186:187], off
	s_waitcnt lgkmcnt(8)
	s_barrier
	s_waitcnt lgkmcnt(0)
	s_waitcnt lgkmcnt(0)
	v_mfma_f32_16x16x32_bf16 v[140:143], v[84:87], v[154:157], v[140:143]
	v_mfma_f32_16x16x32_bf16 v[136:139], v[96:99], v[154:157], v[136:139]
	v_mfma_f32_16x16x32_bf16 v[124:127], v[84:87], v[162:165], v[124:127]
	v_mfma_f32_16x16x32_bf16 v[120:123], v[96:99], v[162:165], v[120:123]
	v_mfma_f32_16x16x32_bf16 v[108:111], v[84:87], v[170:173], v[108:111]
	v_mfma_f32_16x16x32_bf16 v[104:107], v[96:99], v[170:173], v[104:107]
	v_mfma_f32_16x16x32_bf16 v[76:79], v[84:87], v[178:181], v[76:79]
	v_mfma_f32_16x16x32_bf16 v[72:75], v[96:99], v[178:181], v[72:75]
	v_mfma_f32_16x16x32_bf16 v[140:143], v[88:91], v[158:161], v[140:143]
	v_mfma_f32_16x16x32_bf16 v[136:139], v[100:103], v[158:161], v[136:139]
	v_mfma_f32_16x16x32_bf16 v[124:127], v[88:91], v[166:169], v[124:127]
	v_mfma_f32_16x16x32_bf16 v[120:123], v[100:103], v[166:169], v[120:123]
	v_mfma_f32_16x16x32_bf16 v[108:111], v[88:91], v[174:177], v[108:111]
	v_mfma_f32_16x16x32_bf16 v[104:107], v[100:103], v[174:177], v[104:107]
	v_mfma_f32_16x16x32_bf16 v[76:79], v[88:91], v[182:185], v[76:79]
	v_mfma_f32_16x16x32_bf16 v[72:75], v[100:103], v[182:185], v[72:75]
	s_barrier
	s_add_i32 s38, s85, 0x100
	s_add_i32 s0, s2, s78
	v_add_u32_e32 v198, s38, v248
	v_lshl_add_u64 v[202:203], s[76:77], 0, v[146:147]
	s_mov_b32 m0, s0
	ds_read_b128 v[186:189], v198
	ds_read_b128 v[190:193], v198 offset:1024
	ds_read_b128 v[194:197], v198 offset:2048
	ds_read_b128 v[198:201], v198 offset:3072
	global_load_lds_dwordx4 v[202:203], off
	v_lshl_add_u64 v[202:203], s[76:77], 0, v[152:153]
	s_add_i32 m0, s0, 0x2000
	s_nop 0
	global_load_lds_dwordx4 v[202:203], off
	s_barrier
	s_waitcnt lgkmcnt(0)
	s_waitcnt lgkmcnt(0)
	v_mfma_f32_16x16x32_bf16 v[132:135], v[186:189], v[154:157], v[132:135]
	v_mfma_f32_16x16x32_bf16 v[128:131], v[194:197], v[154:157], v[128:131]
	v_mfma_f32_16x16x32_bf16 v[116:119], v[186:189], v[162:165], v[116:119]
	v_mfma_f32_16x16x32_bf16 v[112:115], v[194:197], v[162:165], v[112:115]
	v_mfma_f32_16x16x32_bf16 v[92:95], v[186:189], v[170:173], v[92:95]
	v_mfma_f32_16x16x32_bf16 v[80:83], v[194:197], v[170:173], v[80:83]
	v_mfma_f32_16x16x32_bf16 v[68:71], v[186:189], v[178:181], v[68:71]
	v_mfma_f32_16x16x32_bf16 v[64:67], v[194:197], v[178:181], v[64:67]
	v_mfma_f32_16x16x32_bf16 v[132:135], v[190:193], v[158:161], v[132:135]
	v_mfma_f32_16x16x32_bf16 v[128:131], v[198:201], v[158:161], v[128:131]
	v_mfma_f32_16x16x32_bf16 v[116:119], v[190:193], v[166:169], v[116:119]
	v_mfma_f32_16x16x32_bf16 v[112:115], v[198:201], v[166:169], v[112:115]
	v_mfma_f32_16x16x32_bf16 v[92:95], v[190:193], v[174:177], v[92:95]
	v_mfma_f32_16x16x32_bf16 v[80:83], v[198:201], v[174:177], v[80:83]
	v_mfma_f32_16x16x32_bf16 v[68:71], v[190:193], v[182:185], v[68:71]
	v_mfma_f32_16x16x32_bf16 v[64:67], v[198:201], v[182:185], v[64:67]
	s_mov_b32 m0, s14
	v_lshl_add_u64 v[202:203], s[74:75], 0, v[148:149]
	s_barrier
	ds_read_b128 v[154:157], v249 offset:16384
	ds_read_b128 v[158:161], v249 offset:17408
	ds_read_b128 v[162:165], v249 offset:18432
	ds_read_b128 v[166:169], v249 offset:19456
	ds_read_b128 v[170:173], v249 offset:20480
	ds_read_b128 v[174:177], v249 offset:21504
	ds_read_b128 v[178:181], v249 offset:22528
	ds_read_b128 v[182:185], v249 offset:23552
	global_load_lds_dwordx4 v[202:203], off
	v_lshl_add_u64 v[202:203], s[74:75], 0, v[150:151]
	s_mov_b32 m0, s15
	s_nop 0
	global_load_lds_dwordx4 v[202:203], off
	s_barrier
	s_waitcnt lgkmcnt(0)
	s_waitcnt lgkmcnt(0)
	v_mfma_f32_16x16x32_bf16 v[60:63], v[84:87], v[154:157], v[60:63]
	v_mfma_f32_16x16x32_bf16 v[56:59], v[96:99], v[154:157], v[56:59]
	v_mfma_f32_16x16x32_bf16 v[44:47], v[84:87], v[162:165], v[44:47]
	v_mfma_f32_16x16x32_bf16 v[40:43], v[96:99], v[162:165], v[40:43]
	v_mfma_f32_16x16x32_bf16 v[28:31], v[84:87], v[170:173], v[28:31]
	v_mfma_f32_16x16x32_bf16 v[24:27], v[96:99], v[170:173], v[24:27]
	v_mfma_f32_16x16x32_bf16 v[12:15], v[84:87], v[178:181], v[12:15]
	v_mfma_f32_16x16x32_bf16 v[8:11], v[96:99], v[178:181], v[8:11]
	v_mfma_f32_16x16x32_bf16 v[60:63], v[88:91], v[158:161], v[60:63]
	v_mfma_f32_16x16x32_bf16 v[56:59], v[100:103], v[158:161], v[56:59]
	v_mfma_f32_16x16x32_bf16 v[44:47], v[88:91], v[166:169], v[44:47]
	v_mfma_f32_16x16x32_bf16 v[40:43], v[100:103], v[166:169], v[40:43]
	v_mfma_f32_16x16x32_bf16 v[28:31], v[88:91], v[174:177], v[28:31]
	v_mfma_f32_16x16x32_bf16 v[24:27], v[100:103], v[174:177], v[24:27]
	v_mfma_f32_16x16x32_bf16 v[12:15], v[88:91], v[182:185], v[12:15]
	v_mfma_f32_16x16x32_bf16 v[8:11], v[100:103], v[182:185], v[8:11]
	s_barrier
; #define G_STAGE(bufoff, gbase, voff) do { _Pragma("unroll") for (int _i = 0; _i < 2; ++_i) \
;         __builtin_amdgcn_global_load_lds((const unsigned*)((const char*)(gbase) + (voff)[_i]), (LAS unsigned*)(lds + (bufoff) + ldsw + _i * 8192), 16, 0, 0); } while (0)
; #define G_LDA(dst, b, h) do { _Pragma("unroll") for (int m = 0; m < 4; ++m) _Pragma("unroll") for (int k = 0; k < 2; ++k) dst[m][k] = *(const LAS bf16x8*)(lds + G_SA(b, h) + aoff + m * 2048 + k * 1024); } while (0)
; #define G_LDB(dst, b, h) do { _Pragma("unroll") for (int n = 0; n < 2; ++n) _Pragma("unroll") for (int k = 0; k < 2; ++k) dst[n][k] = *(const LAS bf16x8*)(lds + G_SB(b, h) + boff + n * 2048 + k * 1024); } while (0)
; #define G_MMA(ai, bj, At, Bt) do { __builtin_amdgcn_s_setprio(1); _Pragma("unroll") for (int m = 0; m < 4; ++m) _Pragma("unroll") for (int n = 0; n < 2; ++n) _Pragma("unroll") for (int k = 0; k < 2; ++k) \
;         acc[ai][bj][m][n] = __builtin_amdgcn_mfma_f32_16x16x32_bf16(Bt[n][k], At[m][k], acc[ai][bj][m][n], 0, 0, 0); __builtin_amdgcn_s_setprio(0); } while (0)
; #define G_WAIT_V(n) asm volatile("s_waitcnt vmcnt(" #n ")" ::: "memory")
; #define G_WAIT_L(n) asm volatile("s_waitcnt lgkmcnt(" #n ")" ::: "memory")
; #define G_BAR __builtin_amdgcn_s_barrier()
; #define G_SCHED __builtin_amdgcn_sched_barrier(0)
; template <class J>
; DI void gemm_phase(LAS unsigned char* lds, const J& job) {
;     ...
;       G_STAGE(G_SB(0, 1), b2 + hstepB, voffB);
;       G_WAIT_V(6); G_BAR; G_MMA(1, 1, At, B1); G_BAR;
;       G_LDB(B0, 1, 0); G_SCHED; G_LDA(At, 1, 0); G_STAGE(G_SA(0, 1), a2 + hstepA, voffA);
;       G_WAIT_L(8); G_BAR; G_WAIT_L(0); G_MMA(0, 0, At, B0); G_BAR; G_SCHED;
;       G_LDB(B1, 1, 1); G_STAGE(G_SB(1, 0), b3, voffB);
;       G_BAR; G_WAIT_L(0); G_MMA(0, 1, At, B1); G_BAR;
;       G_LDA(At, 1, 1); G_STAGE(G_SA(1, 0), a3, voffA);
	s_add_u32 s0, s76, 0x1000000
	s_addc_u32 s1, s77, 0
	s_add_i32 s2, s38, s78
	v_lshl_add_u64 v[84:85], s[0:1], 0, v[146:147]
	s_mov_b32 m0, s2
	s_nop 0
	global_load_lds_dwordx4 v[84:85], off
	v_lshl_add_u64 v[84:85], s[0:1], 0, v[152:153]
	s_add_i32 m0, s2, 0x2000
	s_nop 0
	global_load_lds_dwordx4 v[84:85], off
	s_waitcnt vmcnt(6)
	s_barrier
	v_mfma_f32_16x16x32_bf16 v[52:55], v[186:189], v[154:157], v[52:55]
	v_mfma_f32_16x16x32_bf16 v[48:51], v[194:197], v[154:157], v[48:51]
	v_mfma_f32_16x16x32_bf16 v[36:39], v[186:189], v[162:165], v[36:39]
	v_mfma_f32_16x16x32_bf16 v[32:35], v[194:197], v[162:165], v[32:35]
	v_mfma_f32_16x16x32_bf16 v[20:23], v[186:189], v[170:173], v[20:23]
	v_mfma_f32_16x16x32_bf16 v[16:19], v[194:197], v[170:173], v[16:19]
	v_mfma_f32_16x16x32_bf16 v[4:7], v[186:189], v[178:181], v[4:7]
	v_mfma_f32_16x16x32_bf16 v[0:3], v[194:197], v[178:181], v[0:3]
	v_mfma_f32_16x16x32_bf16 v[52:55], v[190:193], v[158:161], v[52:55]
	v_mfma_f32_16x16x32_bf16 v[48:51], v[198:201], v[158:161], v[48:51]
	v_mfma_f32_16x16x32_bf16 v[36:39], v[190:193], v[166:169], v[36:39]
	v_mfma_f32_16x16x32_bf16 v[32:35], v[198:201], v[166:169], v[32:35]
	v_mfma_f32_16x16x32_bf16 v[20:23], v[190:193], v[174:177], v[20:23]
	v_mfma_f32_16x16x32_bf16 v[16:19], v[198:201], v[174:177], v[16:19]
	v_mfma_f32_16x16x32_bf16 v[4:7], v[190:193], v[182:185], v[4:7]
	v_mfma_f32_16x16x32_bf16 v[0:3], v[198:201], v[182:185], v[0:3]
	s_add_i32 s2, s88, 0x100
	v_add_u32_e32 v100, s2, v248
	s_barrier
	ds_read_b128 v[84:87], v100
	ds_read_b128 v[88:91], v100 offset:1024
	ds_read_b128 v[96:99], v100 offset:2048
	ds_read_b128 v[100:103], v100 offset:3072
	s_add_u32 s0, s74, 0x80000
	s_addc_u32 s1, s75, 0
	s_mov_b32 m0, s83
	v_lshl_add_u64 v[186:187], s[0:1], 0, v[148:149]
	ds_read_b128 v[154:157], v249 offset:32768
	ds_read_b128 v[158:161], v249 offset:33792
	ds_read_b128 v[162:165], v249 offset:34816
	ds_read_b128 v[166:169], v249 offset:35840
	ds_read_b128 v[170:173], v249 offset:36864
	ds_read_b128 v[174:177], v249 offset:37888
	ds_read_b128 v[178:181], v249 offset:38912
	ds_read_b128 v[182:185], v249 offset:39936
	global_load_lds_dwordx4 v[186:187], off
	v_lshl_add_u64 v[186:187], s[0:1], 0, v[150:151]
	s_mov_b32 m0, s36
	s_nop 0
	global_load_lds_dwordx4 v[186:187], off
	s_waitcnt lgkmcnt(8)
	s_barrier
	s_waitcnt lgkmcnt(0)
	s_waitcnt lgkmcnt(0)
	v_mfma_f32_16x16x32_bf16 v[140:143], v[84:87], v[154:157], v[140:143]
	v_mfma_f32_16x16x32_bf16 v[136:139], v[96:99], v[154:157], v[136:139]
	v_mfma_f32_16x16x32_bf16 v[124:127], v[84:87], v[162:165], v[124:127]
	v_mfma_f32_16x16x32_bf16 v[120:123], v[96:99], v[162:165], v[120:123]
	v_mfma_f32_16x16x32_bf16 v[108:111], v[84:87], v[170:173], v[108:111]
	v_mfma_f32_16x16x32_bf16 v[104:107], v[96:99], v[170:173], v[104:107]
	v_mfma_f32_16x16x32_bf16 v[76:79], v[84:87], v[178:181], v[76:79]
	v_mfma_f32_16x16x32_bf16 v[72:75], v[96:99], v[178:181], v[72:75]
	v_mfma_f32_16x16x32_bf16 v[140:143], v[88:91], v[158:161], v[140:143]
	v_mfma_f32_16x16x32_bf16 v[136:139], v[100:103], v[158:161], v[136:139]
	v_mfma_f32_16x16x32_bf16 v[124:127], v[88:91], v[166:169], v[124:127]
	v_mfma_f32_16x16x32_bf16 v[120:123], v[100:103], v[166:169], v[120:123]
	v_mfma_f32_16x16x32_bf16 v[108:111], v[88:91], v[174:177], v[108:111]
	v_mfma_f32_16x16x32_bf16 v[104:107], v[100:103], v[174:177], v[104:107]
	v_mfma_f32_16x16x32_bf16 v[76:79], v[88:91], v[182:185], v[76:79]
	v_mfma_f32_16x16x32_bf16 v[72:75], v[100:103], v[182:185], v[72:75]
	s_barrier
	s_add_i32 s38, s89, 0x100
	s_add_i32 s0, s2, s78
	v_add_u32_e32 v198, s38, v248
	v_lshl_add_u64 v[202:203], s[70:71], 0, v[146:147]
	s_mov_b32 m0, s0
	ds_read_b128 v[186:189], v198
	ds_read_b128 v[190:193], v198 offset:1024
	ds_read_b128 v[194:197], v198 offset:2048
	ds_read_b128 v[198:201], v198 offset:3072
	global_load_lds_dwordx4 v[202:203], off
	v_lshl_add_u64 v[202:203], s[70:71], 0, v[152:153]
	s_add_i32 m0, s0, 0x2000
	s_nop 0
	global_load_lds_dwordx4 v[202:203], off
	s_barrier
	s_waitcnt lgkmcnt(0)
	s_waitcnt lgkmcnt(0)
	v_mfma_f32_16x16x32_bf16 v[132:135], v[186:189], v[154:157], v[132:135]
	v_mfma_f32_16x16x32_bf16 v[128:131], v[194:197], v[154:157], v[128:131]
	v_mfma_f32_16x16x32_bf16 v[116:119], v[186:189], v[162:165], v[116:119]
	v_mfma_f32_16x16x32_bf16 v[112:115], v[194:197], v[162:165], v[112:115]
	v_mfma_f32_16x16x32_bf16 v[92:95], v[186:189], v[170:173], v[92:95]
	v_mfma_f32_16x16x32_bf16 v[80:83], v[194:197], v[170:173], v[80:83]
	v_mfma_f32_16x16x32_bf16 v[68:71], v[186:189], v[178:181], v[68:71]
	v_mfma_f32_16x16x32_bf16 v[64:67], v[194:197], v[178:181], v[64:67]
	v_mfma_f32_16x16x32_bf16 v[132:135], v[190:193], v[158:161], v[132:135]
	v_mfma_f32_16x16x32_bf16 v[128:131], v[198:201], v[158:161], v[128:131]
	v_mfma_f32_16x16x32_bf16 v[116:119], v[190:193], v[166:169], v[116:119]
	v_mfma_f32_16x16x32_bf16 v[112:115], v[198:201], v[166:169], v[112:115]
	v_mfma_f32_16x16x32_bf16 v[92:95], v[190:193], v[174:177], v[92:95]
	v_mfma_f32_16x16x32_bf16 v[80:83], v[198:201], v[174:177], v[80:83]
	v_mfma_f32_16x16x32_bf16 v[68:71], v[190:193], v[182:185], v[68:71]
	v_mfma_f32_16x16x32_bf16 v[64:67], v[198:201], v[182:185], v[64:67]
	s_mov_b32 m0, s24
	v_lshl_add_u64 v[202:203], s[72:73], 0, v[148:149]
	s_barrier
	ds_read_b128 v[154:157], v249 offset:49152
	ds_read_b128 v[158:161], v249 offset:50176
	ds_read_b128 v[162:165], v249 offset:51200
	ds_read_b128 v[166:169], v249 offset:52224
	ds_read_b128 v[170:173], v249 offset:53248
	ds_read_b128 v[174:177], v249 offset:54272
	ds_read_b128 v[178:181], v249 offset:55296
	ds_read_b128 v[182:185], v249 offset:56320
	global_load_lds_dwordx4 v[202:203], off
	v_lshl_add_u64 v[202:203], s[72:73], 0, v[150:151]
	s_mov_b32 m0, s25
	s_nop 0
	global_load_lds_dwordx4 v[202:203], off
	s_barrier
; #define G_STAGE(bufoff, gbase, voff) do { _Pragma("unroll") for (int _i = 0; _i < 2; ++_i) \
;         __builtin_amdgcn_global_load_lds((const unsigned*)((const char*)(gbase) + (voff)[_i]), (LAS unsigned*)(lds + (bufoff) + ldsw + _i * 8192), 16, 0, 0); } while (0)
; #define G_MMA(ai, bj, At, Bt) do { __builtin_amdgcn_s_setprio(1); _Pragma("unroll") for (int m = 0; m < 4; ++m) _Pragma("unroll") for (int n = 0; n < 2; ++n) _Pragma("unroll") for (int k = 0; k < 2; ++k) \
;         acc[ai][bj][m][n] = __builtin_amdgcn_mfma_f32_16x16x32_bf16(Bt[n][k], At[m][k], acc[ai][bj][m][n], 0, 0, 0); __builtin_amdgcn_s_setprio(0); } while (0)
; #define G_WAIT_V(n) asm volatile("s_waitcnt vmcnt(" #n ")" ::: "memory")
; #define G_WAIT_L(n) asm volatile("s_waitcnt lgkmcnt(" #n ")" ::: "memory")
; #define G_BAR __builtin_amdgcn_s_barrier()
; #define G_SCHED __builtin_amdgcn_sched_barrier(0)
; template <class J>
; DI void gemm_phase(LAS unsigned char* lds, const J& job) {
;     ...
;       G_BAR; G_WAIT_L(0); G_MMA(1, 0, At, B0); G_BAR; G_SCHED;
;       G_STAGE(G_SB(1, 1), b3 + hstepB, voffB);
;       G_WAIT_V(6); G_BAR; G_MMA(1, 1, At, B1); G_BAR;
	s_waitcnt lgkmcnt(0)
	s_waitcnt lgkmcnt(0)
	v_mfma_f32_16x16x32_bf16 v[60:63], v[84:87], v[154:157], v[60:63]
	v_mfma_f32_16x16x32_bf16 v[56:59], v[96:99], v[154:157], v[56:59]
	v_mfma_f32_16x16x32_bf16 v[44:47], v[84:87], v[162:165], v[44:47]
	v_mfma_f32_16x16x32_bf16 v[40:43], v[96:99], v[162:165], v[40:43]
	v_mfma_f32_16x16x32_bf16 v[28:31], v[84:87], v[170:173], v[28:31]
	v_mfma_f32_16x16x32_bf16 v[24:27], v[96:99], v[170:173], v[24:27]
	v_mfma_f32_16x16x32_bf16 v[12:15], v[84:87], v[178:181], v[12:15]
	v_mfma_f32_16x16x32_bf16 v[8:11], v[96:99], v[178:181], v[8:11]
	v_mfma_f32_16x16x32_bf16 v[60:63], v[88:91], v[158:161], v[60:63]
	v_mfma_f32_16x16x32_bf16 v[56:59], v[100:103], v[158:161], v[56:59]
	v_mfma_f32_16x16x32_bf16 v[44:47], v[88:91], v[166:169], v[44:47]
	v_mfma_f32_16x16x32_bf16 v[40:43], v[100:103], v[166:169], v[40:43]
	v_mfma_f32_16x16x32_bf16 v[28:31], v[88:91], v[174:177], v[28:31]
	v_mfma_f32_16x16x32_bf16 v[24:27], v[100:103], v[174:177], v[24:27]
	v_mfma_f32_16x16x32_bf16 v[12:15], v[88:91], v[182:185], v[12:15]
	v_mfma_f32_16x16x32_bf16 v[8:11], v[100:103], v[182:185], v[8:11]
	s_barrier
	s_add_u32 s0, s70, 0x1000000
	s_addc_u32 s1, s71, 0
	s_add_i32 s2, s38, s78
	v_lshl_add_u64 v[84:85], s[0:1], 0, v[146:147]
	s_mov_b32 m0, s2
	s_nop 0
	global_load_lds_dwordx4 v[84:85], off
	v_lshl_add_u64 v[84:85], s[0:1], 0, v[152:153]
	s_add_i32 m0, s2, 0x2000
	s_nop 0
	global_load_lds_dwordx4 v[84:85], off
	s_waitcnt vmcnt(6)
	s_barrier
	v_mfma_f32_16x16x32_bf16 v[52:55], v[186:189], v[154:157], v[52:55]
	v_mfma_f32_16x16x32_bf16 v[48:51], v[194:197], v[154:157], v[48:51]
	v_mfma_f32_16x16x32_bf16 v[36:39], v[186:189], v[162:165], v[36:39]
	v_mfma_f32_16x16x32_bf16 v[32:35], v[194:197], v[162:165], v[32:35]
	v_mfma_f32_16x16x32_bf16 v[20:23], v[186:189], v[170:173], v[20:23]
	v_mfma_f32_16x16x32_bf16 v[16:19], v[194:197], v[170:173], v[16:19]
	v_mfma_f32_16x16x32_bf16 v[4:7], v[186:189], v[178:181], v[4:7]
	v_mfma_f32_16x16x32_bf16 v[0:3], v[194:197], v[178:181], v[0:3]
	v_mfma_f32_16x16x32_bf16 v[52:55], v[190:193], v[158:161], v[52:55]
	v_mfma_f32_16x16x32_bf16 v[48:51], v[198:201], v[158:161], v[48:51]
	v_mfma_f32_16x16x32_bf16 v[36:39], v[190:193], v[166:169], v[36:39]
	v_mfma_f32_16x16x32_bf16 v[32:35], v[198:201], v[166:169], v[32:35]
	v_mfma_f32_16x16x32_bf16 v[20:23], v[190:193], v[174:177], v[20:23]
	v_mfma_f32_16x16x32_bf16 v[16:19], v[198:201], v[174:177], v[16:19]
	v_mfma_f32_16x16x32_bf16 v[4:7], v[190:193], v[182:185], v[4:7]
	v_mfma_f32_16x16x32_bf16 v[0:3], v[198:201], v[182:185], v[0:3]
	s_add_i32 s6, s6, 2
	s_addk_i32 s56, 0x100
	s_addk_i32 s7, 0x100
	s_cmp_gt_u32 s6, 29
	s_barrier
	s_cbranch_scc0 .LBB0_74
;   DI void epi(const Acc& acc, const Unit& u, int wr, int wc, int fr, int fq) const {
;     const int cc = u.pn * 64 + 16 * wc + 4 * fq;
;     u32x2 zz[2][4][4];
; #pragma unroll
;     for (int ai = 0; ai < 2; ++ai)
; #pragma unroll
;       for (int m = 0; m < 4; ++m) {
;         const u16* zr = Z + (size_t)(u.pm * 256 + ai * HALF + wr * 64 + m * 16 + fr) * NGATE + cc;
; #pragma unroll
;         for (int br = 0; br < 4; ++br) zz[ai][m][br] = *(const u32x2*)(zr + br * 2048);
;       }
;     f32x4 bg[4];
; #pragma unroll
;     for (int br = 0; br < 4; ++br) bg[br] = *(const f32x4*)(bgate + br * 2048 + cc);
;     asm volatile("" ::: "memory");
	v_mov_b32_e32 v84, v247
	v_mov_b32_e32 v85, v246
	s_lshl_b32 s0, s44, 6
	s_or_b32 s0, s0, s96
	v_lshl_add_u32 v84, v84, 2, s0
	s_lshl_b32 s0, s64, 8
	s_add_i32 s0, s0, s37
	v_add_u32_e32 v224, s0, v85
	v_ashrrev_i32_e32 v85, 31, v84
	v_lshlrev_b64 v[154:155], 1, v[84:85]
	v_ashrrev_i32_e32 v225, 31, v224
	v_lshl_add_u64 v[86:87], s[26:27], 0, v[154:155]
	v_lshlrev_b64 v[88:89], 14, v[224:225]
	v_lshl_add_u64 v[88:89], v[86:87], 0, v[88:89]
	v_add_co_u32_e32 v90, vcc, s82, v88
	v_add_u32_e32 v212, 16, v224
	s_nop 0
	v_addc_co_u32_e32 v91, vcc, 0, v89, vcc
	v_ashrrev_i32_e32 v213, 31, v212
	v_add_co_u32_e32 v96, vcc, s92, v88
	v_lshlrev_b64 v[98:99], 14, v[212:213]
	s_nop 0
	v_addc_co_u32_e32 v97, vcc, 0, v89, vcc
	v_lshl_add_u64 v[98:99], v[86:87], 0, v[98:99]
	v_add_co_u32_e32 v100, vcc, s82, v98
	v_add_u32_e32 v202, 32, v224
	s_nop 0
	v_addc_co_u32_e32 v101, vcc, 0, v99, vcc
	global_load_dwordx2 v[230:231], v[90:91], off offset:-4096
	global_load_dwordx2 v[226:227], v[90:91], off
	global_load_dwordx2 v[220:221], v[100:101], off offset:-4096
	global_load_dwordx2 v[214:215], v[100:101], off
	v_add_co_u32_e32 v90, vcc, s92, v98
	v_ashrrev_i32_e32 v203, 31, v202
	s_nop 0
	v_addc_co_u32_e32 v91, vcc, 0, v99, vcc
	global_load_dwordx2 v[232:233], v[88:89], off
	global_load_dwordx2 v[228:229], v[96:97], off
	global_load_dwordx2 v[222:223], v[98:99], off
	global_load_dwordx2 v[216:217], v[90:91], off
	v_lshlrev_b64 v[88:89], 14, v[202:203]
	v_lshl_add_u64 v[88:89], v[86:87], 0, v[88:89]
	v_add_co_u32_e32 v90, vcc, s82, v88
	v_add_u32_e32 v190, 48, v224
	s_nop 0
	v_addc_co_u32_e32 v91, vcc, 0, v89, vcc
	v_ashrrev_i32_e32 v191, 31, v190
	v_add_co_u32_e32 v96, vcc, s92, v88
	v_lshlrev_b64 v[98:99], 14, v[190:191]
	s_nop 0
	v_addc_co_u32_e32 v97, vcc, 0, v89, vcc
	v_lshl_add_u64 v[98:99], v[86:87], 0, v[98:99]
	v_add_co_u32_e32 v100, vcc, s82, v98
	v_add_u32_e32 v184, 0x80, v224
	s_nop 0
	v_addc_co_u32_e32 v101, vcc, 0, v99, vcc
	global_load_dwordx2 v[210:211], v[90:91], off offset:-4096
	global_load_dwordx2 v[206:207], v[90:91], off
	global_load_dwordx2 v[200:201], v[100:101], off offset:-4096
	global_load_dwordx2 v[192:193], v[100:101], off
	v_add_co_u32_e32 v90, vcc, s92, v98
	v_lshl_add_u64 v[84:85], v[84:85], 2, s[12:13]
	v_ashrrev_i32_e32 v185, 31, v184
	v_addc_co_u32_e32 v91, vcc, 0, v99, vcc
	global_load_dwordx4 v[100:103], v[84:85], off
	global_load_dwordx2 v[218:219], v[88:89], off
	global_load_dwordx2 v[208:209], v[96:97], off
	global_load_dwordx2 v[204:205], v[98:99], off
	global_load_dwordx2 v[198:199], v[90:91], off
	v_lshlrev_b64 v[88:89], 14, v[184:185]
	v_lshl_add_u64 v[88:89], v[86:87], 0, v[88:89]
	v_add_co_u32_e32 v90, vcc, s82, v88
	v_add_u32_e32 v174, 0x90, v224
	s_nop 0
	v_addc_co_u32_e32 v91, vcc, 0, v89, vcc
	v_add_co_u32_e32 v156, vcc, s92, v88
	v_ashrrev_i32_e32 v175, 31, v174
	s_nop 0
	v_addc_co_u32_e32 v157, vcc, 0, v89, vcc
	v_add_co_u32_e32 v96, vcc, s82, v84
	v_lshlrev_b64 v[158:159], 14, v[174:175]
	s_nop 0
	v_addc_co_u32_e32 v97, vcc, 0, v85, vcc
	global_load_dwordx4 v[96:99], v[96:97], off
	v_lshl_add_u64 v[158:159], v[86:87], 0, v[158:159]
	v_add_co_u32_e32 v160, vcc, s82, v158
	v_add_u32_e32 v164, 0xa0, v224
	s_nop 0
	v_addc_co_u32_e32 v161, vcc, 0, v159, vcc
	global_load_dwordx2 v[194:195], v[90:91], off offset:-4096
	global_load_dwordx2 v[186:187], v[90:91], off
	global_load_dwordx2 v[180:181], v[160:161], off offset:-4096
	global_load_dwordx2 v[176:177], v[160:161], off
	v_add_co_u32_e32 v90, vcc, s92, v158
	v_ashrrev_i32_e32 v165, 31, v164
	s_nop 0
	v_addc_co_u32_e32 v91, vcc, 0, v159, vcc
	global_load_dwordx2 v[196:197], v[88:89], off
	global_load_dwordx2 v[188:189], v[156:157], off
	global_load_dwordx2 v[182:183], v[158:159], off
	global_load_dwordx2 v[178:179], v[90:91], off
	v_lshlrev_b64 v[88:89], 14, v[164:165]
	v_lshl_add_u64 v[162:163], v[86:87], 0, v[88:89]
	v_add_co_u32_e32 v158, vcc, s82, v162
	v_add_u32_e32 v156, 0xb0, v224
	s_nop 0
	v_addc_co_u32_e32 v159, vcc, 0, v163, vcc
	v_add_co_u32_e32 v168, vcc, s92, v162
	v_ashrrev_i32_e32 v157, 31, v156
	s_nop 0
	v_addc_co_u32_e32 v169, vcc, 0, v163, vcc
	v_add_co_u32_e32 v88, vcc, s54, v84
	v_lshlrev_b64 v[160:161], 14, v[156:157]
	s_nop 0
	v_addc_co_u32_e32 v89, vcc, 0, v85, vcc
	global_load_dwordx4 v[88:91], v[88:89], off
	v_lshl_add_u64 v[250:251], v[86:87], 0, v[160:161]
	v_add_co_u32_e32 v86, vcc, s82, v250
	s_mov_b32 s44, s20
	s_nop 0
	v_addc_co_u32_e32 v87, vcc, 0, v251, vcc
	v_add_co_u32_e32 v84, vcc, s55, v84
	global_load_dwordx2 v[170:171], v[158:159], off offset:-4096
	global_load_dwordx2 v[166:167], v[158:159], off
	global_load_dwordx2 v[160:161], v[86:87], off offset:-4096
	s_nop 0
	global_load_dwordx2 v[158:159], v[86:87], off
	v_addc_co_u32_e32 v85, vcc, 0, v85, vcc
	global_load_dwordx4 v[84:87], v[84:85], off
	v_add_co_u32_e32 v252, vcc, s92, v250
	s_mov_b32 s64, s18
	s_nop 0
	v_addc_co_u32_e32 v253, vcc, 0, v251, vcc
	s_and_b64 vcc, exec, s[8:9]
	s_mov_b64 s[66:67], s[62:63]
	s_mov_b64 s[68:69], s[22:23]
	v_readlane_b32 s0, v255, 23
	s_cmpk_gt_u32 s0, 0xff
	s_cbranch_scc1 .Lds_gate_x
	s_barrier

; DI int my_tid() { int t = threadIdx.x; asm volatile("" : "+v"(t)); return t; }
; DI int my_block() { int b = blockIdx.x; asm volatile("" : "+s"(b)); return b; }
; #define G_STAGE(bufoff, gbase, voff) do { _Pragma("unroll") for (int _i = 0; _i < 2; ++_i) \
;         __builtin_amdgcn_global_load_lds((const unsigned*)((const char*)(gbase) + (voff)[_i]), (LAS unsigned*)(lds + (bufoff) + ldsw + _i * 8192), 16, 0, 0); } while (0)
; #define G_BAR __builtin_amdgcn_s_barrier()
;   DI int brow_of(int R) const { return (R & ~31) + perm32(R & 31); }
;   DI const char* aptr(const Unit& u) const { return (const char*)(h + (size_t)u.pm * 256 * DM); }
;   DI const char* bptr(const Unit& u) const { return (const char*)(winT + (size_t)u.pn * 256 * DM); }
;   DI int brow_of(int R) const { return (R & ~31) + perm32(R & 31); }
; template <class J>
; DI void gemm_phase(LAS unsigned char* lds, const J& job) {
;   const int tid = my_tid(), wid = __builtin_amdgcn_readfirstlane(tid >> 6), lane = tid & 63, wr = wid >> 2, wc = wid & 3, fr = lane & 15, fq = lane >> 4;
;   const int nt = job.nt;
;   unsigned voffA[2], voffB[2];
; #pragma unroll
;   for (int i = 0; i < 2; ++i) { int R, C; stage_rc(tid * 16 + i * 8192, R, C); const int Rb = job.brow_of(R);
;     voffA[i] = (unsigned)(R * job.lda + C) * 2u; voffB[i] = (unsigned)(Rb * job.ldb + C) * 2u; }
;   const size_t kstep = (size_t)(BK * 2);
;   const size_t hstepA = (size_t)HALF * job.lda * 2, hstepB = (size_t)job.bhalf_rows() * job.ldb * 2;
;   const unsigned ldsw = (unsigned)wid * 1024u;
;   const int aoff = lds_byte(wr * 64 + fr, fq * 8), boff = lds_byte(wc * 32 + fr, fq * 8);
;     ...
;   Unit cur, nxt; int ui = 0;
;   if (!job.next(0, cur)) return;
;   f32x4 acc[2][2][4][2];
; #pragma unroll
;   for (int a = 0; a < 2; ++a)
; #pragma unroll
;     for (int b = 0; b < 2; ++b)
; #pragma unroll
;       for (int m = 0; m < 4; ++m)
; #pragma unroll
;         for (int n = 0; n < 2; ++n) acc[a][b][m][n] = (f32x4){0.f, 0.f, 0.f, 0.f};
;   bf16x8 At[4][2], B0[2][2], B1[2][2];
;   const char* cA = job.aptr(cur); const char* cB = job.bptr(cur);
;   const int koff = (my_block() & 7) * (nt >> 3), kmask = nt - 1;
;     ...
;   G_STAGE(G_SB(0, 0), cB + G_KT(0), voffB); G_STAGE(G_SA(0, 0), cA + G_KT(0), voffA); G_STAGE(G_SB(0, 1), cB + hstepB + G_KT(0), voffB); G_STAGE(G_SA(0, 1), cA + hstepA + G_KT(0), voffA);
;   if (wr == 1) G_BAR;
.LBB0_96:
	s_andn2_b64 vcc, exec, s[8:9]
	s_cbranch_vccnz .LBB0_109
	v_mov_b32_e32 v0, v144
	s_cmpk_gt_i32 s43, 0x81f
	v_readfirstlane_b32 s4, v0
	s_cbranch_scc1 .LBB0_109
	v_lshlrev_b32_e32 v1, 4, v0
	v_add_u32_e32 v2, 0x2000, v1
	v_ashrrev_i32_e32 v3, 31, v2
	v_lshrrev_b32_e32 v3, 22, v3
	v_add_u32_e32 v3, v2, v3
	v_ashrrev_i32_e32 v3, 10, v3
	s_waitcnt vmcnt(0)
	v_mul_i32_i24_e32 v4, 0x400, v3
	v_sub_u32_e32 v2, v2, v4
	v_writelane_b32 v255, s87, 22
	v_lshrrev_b32_e32 v4, 4, v2
	v_writelane_b32 v255, s36, 20
	v_bitop3_b32 v2, v4, v2, 32 bitop3:0x6c
	v_ashrrev_i32_e32 v4, 31, v2
	v_writelane_b32 v255, s37, 21
	v_lshrrev_b32_e32 v4, 26, v4
	v_readlane_b32 s0, v255, 14
	v_readlane_b32 s1, v255, 15
	v_add_u32_e32 v4, v2, v4
	v_lshlrev_b32_e32 v6, 3, v3
	s_and_b64 s[6:7], s[0:1], exec
	v_ashrrev_i32_e32 v5, 6, v4
	v_and_b32_e32 v6, -16, v6
	v_and_b32_e32 v4, 0xc0, v4
	s_cselect_b32 s0, 0x800000, 0
	v_add_u32_e32 v5, v5, v6
	v_sub_u32_e32 v2, v2, v4
	s_add_u32 s14, s52, s0
	v_lshrrev_b32_e32 v7, 2, v5
	v_lshlrev_b32_e32 v8, 1, v5
	v_lshlrev_b32_e32 v3, 5, v3
	v_ashrrev_i16_sdwa v2, v220, sext(v2) dst_sel:DWORD dst_unused:UNUSED_PAD src0_sel:DWORD src1_sel:BYTE_0
	s_addc_u32 s15, s53, 0
	v_and_b32_e32 v6, 0x3fffe3, v5
	v_and_b32_e32 v7, 4, v7
	v_and_b32_e32 v8, 24, v8
	v_and_b32_e32 v3, 32, v3
	v_bfe_i32 v2, v2, 0, 16
	s_ashr_i32 s0, s43, 31
	v_or3_b32 v6, v6, v7, v8
	v_add_lshl_u32 v2, v3, v2, 1
	s_lshr_b32 s0, s0, 29
	v_lshl_add_u32 v128, v6, 10, v2
	v_lshl_add_u32 v130, v5, 12, v2
	v_bfe_i32 v2, v0, 27, 1
	s_add_i32 s0, s43, s0
	s_ashr_i32 s5, s4, 6
	v_lshrrev_b32_e32 v2, 22, v2
	s_and_b32 s1, s0, -8
	s_ashr_i32 s6, s4, 8
	s_lshl_b32 s24, s5, 10
	v_add_u32_e32 v2, v1, v2
	s_sub_i32 s1, s43, s1
	v_and_b32_e32 v2, 0xfffffc00, v2
	s_cmp_lt_i32 s1, 0
	s_movk_i32 s7, 0x105
	v_sub_u32_e32 v1, v1, v2
	v_ashrrev_i32_e32 v3, 31, v0
	s_cselect_b32 s7, s7, 0x104
	v_lshrrev_b32_e32 v2, 4, v1
	v_lshrrev_b32_e32 v3, 26, v3
	s_mul_i32 s1, s7, s1
	s_ashr_i32 s0, s0, 3
	v_bitop3_b32 v2, v2, v1, 32 bitop3:0x6c
	v_ashrrev_i32_e32 v1, 31, v1
	v_add_u32_e32 v3, v0, v3
	s_add_i32 s0, s1, s0
	v_lshrrev_b32_e32 v1, 26, v1
	v_ashrrev_i32_e32 v3, 6, v3
	s_ashr_i32 s1, s0, 31
	v_add_u32_e32 v1, v2, v1
	v_lshlrev_b32_e32 v4, 3, v3
	s_lshr_b32 s1, s1, 24
	v_ashrrev_i32_e32 v1, 6, v1
	v_and_b32_e32 v4, -16, v4
	s_add_i32 s1, s0, s1
	v_add_u32_e32 v4, v1, v4
	v_mul_i32_i24_e32 v1, 64, v1
	s_ashr_i32 s1, s1, 8
	v_sub_u32_e32 v1, v2, v1
	s_lshl_b32 s7, s1, 3
	v_lshrrev_b32_e32 v6, 2, v4
	v_lshlrev_b32_e32 v7, 1, v4
	v_lshlrev_b32_e32 v3, 5, v3
	v_ashrrev_i16_sdwa v1, v220, sext(v1) dst_sel:DWORD dst_unused:UNUSED_PAD src0_sel:DWORD src1_sel:BYTE_0
	s_sub_i32 s8, 0x41, s7
	s_lshl_b32 s1, s1, 8
	v_and_b32_e32 v5, 0x3fffe3, v4
	v_and_b32_e32 v6, 4, v6
	v_and_b32_e32 v7, 24, v7
	v_and_b32_e32 v3, 32, v3
	v_bfe_i32 v1, v1, 0, 16
	s_min_u32 s12, s8, 8
	s_sub_i32 s0, s0, s1
	v_or3_b32 v5, v5, v6, v7
	v_add_lshl_u32 v1, v3, v1, 1
	s_sext_i32_i16 s1, s0
	v_cvt_f32_ubyte0_e32 v3, s12
	v_lshl_add_u32 v146, v5, 10, v1
	v_cvt_f32_i32_e32 v2, s1
	v_rcp_iflag_f32_e32 v5, v3
	v_lshl_add_u32 v132, v4, 12, v1
	s_ashr_i32 s1, s1, 30
	s_or_b32 s1, s1, 1
	v_mul_f32_e32 v1, v2, v5
	v_trunc_f32_e32 v1, v1
	v_fma_f32 v2, -v1, v3, v2
	v_cvt_i32_f32_e32 v1, v1
	v_cmp_ge_f32_e64 s[8:9], |v2|, v3
	s_and_b64 s[8:9], s[8:9], exec
	s_cselect_b32 s1, s1, 0
	v_readfirstlane_b32 s8, v1
	s_add_i32 s8, s8, s1
	s_mul_i32 s1, s8, s12
	s_sub_i32 s0, s0, s1
	s_sext_i32_i16 s46, s8
	s_sext_i32_i16 s0, s0
	s_add_i32 s22, s7, s0
	s_lshl_b32 s0, s46, 6
	s_ashr_i32 s23, s22, 31
	s_and_b32 s16, s0, 0xfffffe00
	s_bfe_i64 s[8:9], s[8:9], 0x100000
	s_lshl_b64 s[12:13], s[22:23], 20
	s_ashr_i32 s17, s16, 31
	s_lshl_b64 s[8:9], s[8:9], 18
	s_add_u32 s62, s14, s8
	s_mov_b32 s7, s2
	s_addc_u32 s63, s15, s9
	s_and_b32 s0, s7, 7
	s_lshl_b32 s23, s0, 7
	s_add_u32 s8, s62, s23
	s_addc_u32 s9, s63, 0
	s_add_i32 s25, s24, 0x100
	s_add_i32 m0, s25, 0x10000
	s_nop 0
	global_load_lds_dwordx4 v146, s[8:9]
	s_add_i32 m0, s25, 0x12000
	s_add_u32 s0, s10, s12
	global_load_lds_dwordx4 v128, s[8:9]
	s_addc_u32 s1, s11, s13
	s_lshl_b64 s[8:9], s[16:17], 1
	s_add_u32 s64, s0, s8
	s_addc_u32 s65, s1, s9
	s_add_u32 s12, s64, s23
	s_addc_u32 s13, s65, 0
	s_add_i32 s36, s25, 0x2000
	s_add_u32 s8, s62, 0x20000
	s_mov_b32 m0, s25
	s_addc_u32 s9, s63, 0
	global_load_lds_dwordx4 v132, s[12:13]
	s_mov_b32 m0, s36
	s_add_u32 s16, s8, s23
	global_load_lds_dwordx4 v130, s[12:13]
	s_addc_u32 s17, s9, 0
	s_add_i32 m0, s25, 0x14000
	s_nop 0
	global_load_lds_dwordx4 v146, s[16:17]
	s_add_i32 m0, s25, 0x16000
	s_add_u32 s12, s12, 0x80000
	s_addc_u32 s13, s13, 0
	s_add_i32 s37, s25, 0x4000
	global_load_lds_dwordx4 v128, s[16:17]
	s_mov_b32 m0, s37
	s_add_i32 s38, s25, 0x6000
	global_load_lds_dwordx4 v132, s[12:13]
	s_mov_b32 m0, s38
	s_cmp_lg_u32 s6, 1
	global_load_lds_dwordx4 v130, s[12:13]
	s_cbranch_scc1 .LBB0_100
	s_barrier
	s_setprio 1

; #define G_STAGE(bufoff, gbase, voff) do { _Pragma("unroll") for (int _i = 0; _i < 2; ++_i) \
;         __builtin_amdgcn_global_load_lds((const unsigned*)((const char*)(gbase) + (voff)[_i]), (LAS unsigned*)(lds + (bufoff) + ldsw + _i * 8192), 16, 0, 0); } while (0)
; #define G_LDA(dst, b, h) do { _Pragma("unroll") for (int m = 0; m < 4; ++m) _Pragma("unroll") for (int k = 0; k < 2; ++k) dst[m][k] = *(const LAS bf16x8*)(lds + G_SA(b, h) + aoff + m * 2048 + k * 1024); } while (0)
; #define G_LDB(dst, b, h) do { _Pragma("unroll") for (int n = 0; n < 2; ++n) _Pragma("unroll") for (int k = 0; k < 2; ++k) dst[n][k] = *(const LAS bf16x8*)(lds + G_SB(b, h) + boff + n * 2048 + k * 1024); } while (0)
; #define G_MMA(ai, bj, At, Bt) do { __builtin_amdgcn_s_setprio(1); _Pragma("unroll") for (int m = 0; m < 4; ++m) _Pragma("unroll") for (int n = 0; n < 2; ++n) _Pragma("unroll") for (int k = 0; k < 2; ++k) \
;         acc[ai][bj][m][n] = __builtin_amdgcn_mfma_f32_16x16x32_bf16(Bt[n][k], At[m][k], acc[ai][bj][m][n], 0, 0, 0); __builtin_amdgcn_s_setprio(0); } while (0)
; #define G_WAIT_L(n) asm volatile("s_waitcnt lgkmcnt(" #n ")" ::: "memory")
; #define G_BAR __builtin_amdgcn_s_barrier()
; #define G_SCHED __builtin_amdgcn_sched_barrier(0)
;   DI const char* aptr(const Unit& u) const { return (const char*)(h + (size_t)u.pm * 256 * DM); }
; template <class J>
; DI void gemm_phase(LAS unsigned char* lds, const J& job) {
;     ...
;     const bool has_next = job.next(ui + 1, nxt);
;     const char* nA = has_next ? job.aptr(nxt) : cA; const char* nB = has_next ? job.bptr(nxt) : cB;
;     for (int t = 0; t < nt; t += 2) {
;       const bool last = (t == nt - 2);
;       const char* a1 = cA + G_KT(t + 1);
;       const char* a2 = last ? nA + G_KT(0) : cA + G_KT(t + 2); const char* b2 = last ? nB + G_KT(0) : cB + G_KT(t + 2);
;       const char* a3 = last ? nA + G_KT(1) : cA + G_KT(t + 3); const char* b3 = last ? nB + G_KT(1) : cB + G_KT(t + 3);
;       G_LDB(B0, 0, 0); G_SCHED; G_LDA(At, 0, 0); G_STAGE(G_SA(1, 1), a1 + hstepA, voffA);
;       G_WAIT_L(8); G_BAR; G_WAIT_L(0); G_MMA(0, 0, At, B0); G_BAR; G_SCHED;
;       G_LDB(B1, 0, 1); G_STAGE(G_SB(0, 0), b2, voffB);
;       G_BAR; G_WAIT_L(0); G_MMA(0, 1, At, B1); G_BAR;
;       G_LDA(At, 0, 1); G_STAGE(G_SA(0, 0), a2, voffA);
;       G_BAR; G_WAIT_L(0); G_MMA(1, 0, At, B0); G_BAR; G_SCHED;
.LBB0_104:
	s_add_i32 s1, s56, 0xffffff80
	s_and_b32 s0, s7, 0x380
	s_and_b32 s1, s1, 0x380
	s_add_u32 s57, s64, s1
	s_addc_u32 s66, s65, 0
	s_add_u32 s1, s62, s1
	s_addc_u32 s67, s63, 0
	s_and_b32 s68, s56, 0x380
	s_add_u32 s80, s64, s68
	s_addc_u32 s69, s65, 0
	s_add_u32 s97, s62, s68
	s_addc_u32 vcc_lo, s63, 0
	s_cmp_eq_u32 s6, 4
	s_cselect_b32 s71, s83, s66
	s_cselect_b32 s70, s47, s57
	s_cselect_b32 s73, s87, s67
	s_cselect_b32 s72, s86, s1
	s_cselect_b32 s69, s94, s69
	s_cselect_b32 s68, s33, s80
	s_cselect_b32 s67, s5, vcc_lo
	s_cselect_b32 s66, s96, s97
	s_add_i32 s1, s84, 0x100
	v_add_u32_e32 v134, s1, v138
	ds_read_b128 v[140:143], v134
	ds_read_b128 v[148:151], v134 offset:1024
	ds_read_b128 v[152:155], v134 offset:2048
	ds_read_b128 v[156:159], v134 offset:3072
	s_add_u32 vcc_lo, s9, s0
	s_addc_u32 vcc_hi, s17, 0
	v_lshl_add_u64 v[134:135], vcc, 0, v[132:133]
	s_add_i32 m0, s25, 0xc000
	ds_read_b128 v[160:163], v139
	ds_read_b128 v[164:167], v139 offset:1024
	ds_read_b128 v[168:171], v139 offset:2048
	ds_read_b128 v[172:175], v139 offset:3072
	ds_read_b128 v[176:179], v139 offset:4096
	ds_read_b128 v[180:183], v139 offset:5120
	ds_read_b128 v[184:187], v139 offset:6144
	ds_read_b128 v[188:191], v139 offset:7168
	global_load_lds_dwordx4 v[134:135], off
	v_lshl_add_u64 v[134:135], vcc, 0, v[130:131]
	s_add_i32 m0, s25, 0xe000
	s_nop 0
	global_load_lds_dwordx4 v[134:135], off
	s_waitcnt lgkmcnt(8)
	s_barrier
	s_waitcnt lgkmcnt(0)
	s_waitcnt lgkmcnt(0)
	v_mfma_f32_16x16x32_bf16 v[124:127], v[140:143], v[160:163], v[124:127]
	v_mfma_f32_16x16x32_bf16 v[120:123], v[152:155], v[160:163], v[120:123]
	v_mfma_f32_16x16x32_bf16 v[116:119], v[140:143], v[168:171], v[116:119]
	v_mfma_f32_16x16x32_bf16 v[108:111], v[152:155], v[168:171], v[108:111]
	v_mfma_f32_16x16x32_bf16 v[100:103], v[140:143], v[176:179], v[100:103]
	v_mfma_f32_16x16x32_bf16 v[92:95], v[152:155], v[176:179], v[92:95]
	v_mfma_f32_16x16x32_bf16 v[84:87], v[140:143], v[184:187], v[84:87]
	v_mfma_f32_16x16x32_bf16 v[76:79], v[152:155], v[184:187], v[76:79]
	v_mfma_f32_16x16x32_bf16 v[124:127], v[148:151], v[164:167], v[124:127]
	v_mfma_f32_16x16x32_bf16 v[120:123], v[156:159], v[164:167], v[120:123]
	v_mfma_f32_16x16x32_bf16 v[116:119], v[148:151], v[172:175], v[116:119]
	v_mfma_f32_16x16x32_bf16 v[108:111], v[156:159], v[172:175], v[108:111]
	v_mfma_f32_16x16x32_bf16 v[100:103], v[148:151], v[180:183], v[100:103]
	v_mfma_f32_16x16x32_bf16 v[92:95], v[156:159], v[180:183], v[92:95]
	v_mfma_f32_16x16x32_bf16 v[84:87], v[148:151], v[188:191], v[84:87]
	v_mfma_f32_16x16x32_bf16 v[76:79], v[156:159], v[188:191], v[76:79]
	s_barrier
	s_add_i32 s0, s85, 0x100
	v_add_u32_e32 v134, s0, v138
	s_add_i32 s1, s1, s24
	ds_read_b128 v[192:195], v134
	ds_read_b128 v[196:199], v134 offset:1024
	ds_read_b128 v[200:203], v134 offset:2048
	ds_read_b128 v[204:207], v134 offset:3072
	v_lshl_add_u64 v[134:135], s[72:73], 0, v[146:147]
	s_mov_b32 m0, s1
	s_nop 0
	global_load_lds_dwordx4 v[134:135], off
	v_lshl_add_u64 v[134:135], s[72:73], 0, v[128:129]
	s_add_i32 m0, s1, 0x2000
	s_nop 0
	global_load_lds_dwordx4 v[134:135], off
	s_barrier
	s_waitcnt lgkmcnt(0)
	s_waitcnt lgkmcnt(0)
	v_mfma_f32_16x16x32_bf16 v[112:115], v[192:195], v[160:163], v[112:115]
	v_mfma_f32_16x16x32_bf16 v[104:107], v[200:203], v[160:163], v[104:107]
	v_mfma_f32_16x16x32_bf16 v[96:99], v[192:195], v[168:171], v[96:99]
	v_mfma_f32_16x16x32_bf16 v[88:91], v[200:203], v[168:171], v[88:91]
	v_mfma_f32_16x16x32_bf16 v[80:83], v[192:195], v[176:179], v[80:83]
	v_mfma_f32_16x16x32_bf16 v[72:75], v[200:203], v[176:179], v[72:75]
	v_mfma_f32_16x16x32_bf16 v[68:71], v[192:195], v[184:187], v[68:71]
	v_mfma_f32_16x16x32_bf16 v[64:67], v[200:203], v[184:187], v[64:67]
	v_mfma_f32_16x16x32_bf16 v[112:115], v[196:199], v[164:167], v[112:115]
	v_mfma_f32_16x16x32_bf16 v[104:107], v[204:207], v[164:167], v[104:107]
	v_mfma_f32_16x16x32_bf16 v[96:99], v[196:199], v[172:175], v[96:99]
	v_mfma_f32_16x16x32_bf16 v[88:91], v[204:207], v[172:175], v[88:91]
	v_mfma_f32_16x16x32_bf16 v[80:83], v[196:199], v[180:183], v[80:83]
	v_mfma_f32_16x16x32_bf16 v[72:75], v[204:207], v[180:183], v[72:75]
	v_mfma_f32_16x16x32_bf16 v[68:71], v[196:199], v[188:191], v[68:71]
	v_mfma_f32_16x16x32_bf16 v[64:67], v[204:207], v[188:191], v[64:67]
	s_mov_b32 m0, s25
	v_lshl_add_u64 v[134:135], s[70:71], 0, v[132:133]
	s_barrier
	ds_read_b128 v[160:163], v139 offset:16384
	ds_read_b128 v[164:167], v139 offset:17408
	ds_read_b128 v[168:171], v139 offset:18432
	ds_read_b128 v[172:175], v139 offset:19456
	ds_read_b128 v[176:179], v139 offset:20480
	ds_read_b128 v[180:183], v139 offset:21504
	ds_read_b128 v[184:187], v139 offset:22528
	ds_read_b128 v[188:191], v139 offset:23552
	global_load_lds_dwordx4 v[134:135], off
	v_lshl_add_u64 v[134:135], s[70:71], 0, v[130:131]
	s_mov_b32 m0, s36
	s_nop 0
	global_load_lds_dwordx4 v[134:135], off
	s_barrier
	s_waitcnt lgkmcnt(0)
	s_waitcnt lgkmcnt(0)
	v_mfma_f32_16x16x32_bf16 v[60:63], v[140:143], v[160:163], v[60:63]
	v_mfma_f32_16x16x32_bf16 v[56:59], v[152:155], v[160:163], v[56:59]
	v_mfma_f32_16x16x32_bf16 v[52:55], v[140:143], v[168:171], v[52:55]
	v_mfma_f32_16x16x32_bf16 v[44:47], v[152:155], v[168:171], v[44:47]
	v_mfma_f32_16x16x32_bf16 v[36:39], v[140:143], v[176:179], v[36:39]
	v_mfma_f32_16x16x32_bf16 v[28:31], v[152:155], v[176:179], v[28:31]
	v_mfma_f32_16x16x32_bf16 v[20:23], v[140:143], v[184:187], v[20:23]
	v_mfma_f32_16x16x32_bf16 v[12:15], v[152:155], v[184:187], v[12:15]
	v_mfma_f32_16x16x32_bf16 v[60:63], v[148:151], v[164:167], v[60:63]
	v_mfma_f32_16x16x32_bf16 v[56:59], v[156:159], v[164:167], v[56:59]
	v_mfma_f32_16x16x32_bf16 v[52:55], v[148:151], v[172:175], v[52:55]
	v_mfma_f32_16x16x32_bf16 v[44:47], v[156:159], v[172:175], v[44:47]
	v_mfma_f32_16x16x32_bf16 v[36:39], v[148:151], v[180:183], v[36:39]
	v_mfma_f32_16x16x32_bf16 v[28:31], v[156:159], v[180:183], v[28:31]
	v_mfma_f32_16x16x32_bf16 v[20:23], v[148:151], v[188:191], v[20:23]
	v_mfma_f32_16x16x32_bf16 v[12:15], v[156:159], v[188:191], v[12:15]
	s_barrier
; #define G_STAGE(bufoff, gbase, voff) do { _Pragma("unroll") for (int _i = 0; _i < 2; ++_i) \
;         __builtin_amdgcn_global_load_lds((const unsigned*)((const char*)(gbase) + (voff)[_i]), (LAS unsigned*)(lds + (bufoff) + ldsw + _i * 8192), 16, 0, 0); } while (0)
; #define G_LDA(dst, b, h) do { _Pragma("unroll") for (int m = 0; m < 4; ++m) _Pragma("unroll") for (int k = 0; k < 2; ++k) dst[m][k] = *(const LAS bf16x8*)(lds + G_SA(b, h) + aoff + m * 2048 + k * 1024); } while (0)
; #define G_LDB(dst, b, h) do { _Pragma("unroll") for (int n = 0; n < 2; ++n) _Pragma("unroll") for (int k = 0; k < 2; ++k) dst[n][k] = *(const LAS bf16x8*)(lds + G_SB(b, h) + boff + n * 2048 + k * 1024); } while (0)
; #define G_MMA(ai, bj, At, Bt) do { __builtin_amdgcn_s_setprio(1); _Pragma("unroll") for (int m = 0; m < 4; ++m) _Pragma("unroll") for (int n = 0; n < 2; ++n) _Pragma("unroll") for (int k = 0; k < 2; ++k) \
;         acc[ai][bj][m][n] = __builtin_amdgcn_mfma_f32_16x16x32_bf16(Bt[n][k], At[m][k], acc[ai][bj][m][n], 0, 0, 0); __builtin_amdgcn_s_setprio(0); } while (0)
; #define G_WAIT_V(n) asm volatile("s_waitcnt vmcnt(" #n ")" ::: "memory")
; #define G_WAIT_L(n) asm volatile("s_waitcnt lgkmcnt(" #n ")" ::: "memory")
; #define G_BAR __builtin_amdgcn_s_barrier()
; #define G_SCHED __builtin_amdgcn_sched_barrier(0)
; template <class J>
; DI void gemm_phase(LAS unsigned char* lds, const J& job) {
;     ...
;       G_STAGE(G_SB(0, 1), b2 + hstepB, voffB);
;       G_WAIT_V(6); G_BAR; G_MMA(1, 1, At, B1); G_BAR;
;       G_LDB(B0, 1, 0); G_SCHED; G_LDA(At, 1, 0); G_STAGE(G_SA(0, 1), a2 + hstepA, voffA);
;       G_WAIT_L(8); G_BAR; G_WAIT_L(0); G_MMA(0, 0, At, B0); G_BAR; G_SCHED;
;       G_LDB(B1, 1, 1); G_STAGE(G_SB(1, 0), b3, voffB);
;       G_BAR; G_WAIT_L(0); G_MMA(0, 1, At, B1); G_BAR;
;       G_LDA(At, 1, 1); G_STAGE(G_SA(1, 0), a3, voffA);
	s_add_u32 s72, s72, 0x20000
	s_addc_u32 s73, s73, 0
	s_add_i32 s0, s0, s24
	v_lshl_add_u64 v[134:135], s[72:73], 0, v[146:147]
	s_mov_b32 m0, s0
	s_nop 0
	global_load_lds_dwordx4 v[134:135], off
	v_lshl_add_u64 v[134:135], s[72:73], 0, v[128:129]
	s_add_i32 m0, s0, 0x2000
	s_nop 0
	global_load_lds_dwordx4 v[134:135], off
	s_waitcnt vmcnt(6)
	s_barrier
	v_mfma_f32_16x16x32_bf16 v[48:51], v[192:195], v[160:163], v[48:51]
	v_mfma_f32_16x16x32_bf16 v[40:43], v[200:203], v[160:163], v[40:43]
	v_mfma_f32_16x16x32_bf16 v[32:35], v[192:195], v[168:171], v[32:35]
	v_mfma_f32_16x16x32_bf16 v[24:27], v[200:203], v[168:171], v[24:27]
	v_mfma_f32_16x16x32_bf16 v[16:19], v[192:195], v[176:179], v[16:19]
	v_mfma_f32_16x16x32_bf16 v[8:11], v[200:203], v[176:179], v[8:11]
	v_mfma_f32_16x16x32_bf16 v[4:7], v[192:195], v[184:187], v[4:7]
	v_mfma_f32_16x16x32_bf16 v[0:3], v[200:203], v[184:187], v[0:3]
	v_mfma_f32_16x16x32_bf16 v[48:51], v[196:199], v[164:167], v[48:51]
	v_mfma_f32_16x16x32_bf16 v[40:43], v[204:207], v[164:167], v[40:43]
	v_mfma_f32_16x16x32_bf16 v[32:35], v[196:199], v[172:175], v[32:35]
	v_mfma_f32_16x16x32_bf16 v[24:27], v[204:207], v[172:175], v[24:27]
	v_mfma_f32_16x16x32_bf16 v[16:19], v[196:199], v[180:183], v[16:19]
	v_mfma_f32_16x16x32_bf16 v[8:11], v[204:207], v[180:183], v[8:11]
	v_mfma_f32_16x16x32_bf16 v[4:7], v[196:199], v[188:191], v[4:7]
	v_mfma_f32_16x16x32_bf16 v[0:3], v[204:207], v[188:191], v[0:3]
	s_add_i32 s0, s88, 0x100
	v_add_u32_e32 v134, s0, v138
	s_barrier
	ds_read_b128 v[140:143], v134
	ds_read_b128 v[148:151], v134 offset:1024
	ds_read_b128 v[152:155], v134 offset:2048
	ds_read_b128 v[156:159], v134 offset:3072
	s_add_u32 s70, s70, 0x80000
	s_addc_u32 s71, s71, 0
	s_mov_b32 m0, s37
	v_lshl_add_u64 v[134:135], s[70:71], 0, v[132:133]
	ds_read_b128 v[160:163], v139 offset:32768
	ds_read_b128 v[164:167], v139 offset:33792
	ds_read_b128 v[168:171], v139 offset:34816
	ds_read_b128 v[172:175], v139 offset:35840
	ds_read_b128 v[176:179], v139 offset:36864
	ds_read_b128 v[180:183], v139 offset:37888
	ds_read_b128 v[184:187], v139 offset:38912
	ds_read_b128 v[188:191], v139 offset:39936
	global_load_lds_dwordx4 v[134:135], off
	v_lshl_add_u64 v[134:135], s[70:71], 0, v[130:131]
	s_mov_b32 m0, s38
	s_nop 0
	global_load_lds_dwordx4 v[134:135], off
	s_waitcnt lgkmcnt(8)
	s_barrier
	s_waitcnt lgkmcnt(0)
	s_waitcnt lgkmcnt(0)
	v_mfma_f32_16x16x32_bf16 v[124:127], v[140:143], v[160:163], v[124:127]
	v_mfma_f32_16x16x32_bf16 v[120:123], v[152:155], v[160:163], v[120:123]
	v_mfma_f32_16x16x32_bf16 v[116:119], v[140:143], v[168:171], v[116:119]
	v_mfma_f32_16x16x32_bf16 v[108:111], v[152:155], v[168:171], v[108:111]
	v_mfma_f32_16x16x32_bf16 v[100:103], v[140:143], v[176:179], v[100:103]
	v_mfma_f32_16x16x32_bf16 v[92:95], v[152:155], v[176:179], v[92:95]
	v_mfma_f32_16x16x32_bf16 v[84:87], v[140:143], v[184:187], v[84:87]
	v_mfma_f32_16x16x32_bf16 v[76:79], v[152:155], v[184:187], v[76:79]
	v_mfma_f32_16x16x32_bf16 v[124:127], v[148:151], v[164:167], v[124:127]
	v_mfma_f32_16x16x32_bf16 v[120:123], v[156:159], v[164:167], v[120:123]
	v_mfma_f32_16x16x32_bf16 v[116:119], v[148:151], v[172:175], v[116:119]
	v_mfma_f32_16x16x32_bf16 v[108:111], v[156:159], v[172:175], v[108:111]
	v_mfma_f32_16x16x32_bf16 v[100:103], v[148:151], v[180:183], v[100:103]
	v_mfma_f32_16x16x32_bf16 v[92:95], v[156:159], v[180:183], v[92:95]
	v_mfma_f32_16x16x32_bf16 v[84:87], v[148:151], v[188:191], v[84:87]
	v_mfma_f32_16x16x32_bf16 v[76:79], v[156:159], v[188:191], v[76:79]
	s_barrier
	s_add_i32 s1, s89, 0x100
	v_add_u32_e32 v134, s1, v138
	s_add_i32 s0, s0, s24
	ds_read_b128 v[192:195], v134
	ds_read_b128 v[196:199], v134 offset:1024
	ds_read_b128 v[200:203], v134 offset:2048
	ds_read_b128 v[204:207], v134 offset:3072
	v_lshl_add_u64 v[134:135], s[66:67], 0, v[146:147]
	s_mov_b32 m0, s0
	s_nop 0
	global_load_lds_dwordx4 v[134:135], off
	v_lshl_add_u64 v[134:135], s[66:67], 0, v[128:129]
	s_add_i32 m0, s0, 0x2000
	s_nop 0
	global_load_lds_dwordx4 v[134:135], off
	s_barrier
	s_waitcnt lgkmcnt(0)
	s_waitcnt lgkmcnt(0)
	v_mfma_f32_16x16x32_bf16 v[112:115], v[192:195], v[160:163], v[112:115]
	v_mfma_f32_16x16x32_bf16 v[104:107], v[200:203], v[160:163], v[104:107]
	v_mfma_f32_16x16x32_bf16 v[96:99], v[192:195], v[168:171], v[96:99]
	v_mfma_f32_16x16x32_bf16 v[88:91], v[200:203], v[168:171], v[88:91]
	v_mfma_f32_16x16x32_bf16 v[80:83], v[192:195], v[176:179], v[80:83]
	v_mfma_f32_16x16x32_bf16 v[72:75], v[200:203], v[176:179], v[72:75]
	v_mfma_f32_16x16x32_bf16 v[68:71], v[192:195], v[184:187], v[68:71]
	v_mfma_f32_16x16x32_bf16 v[64:67], v[200:203], v[184:187], v[64:67]
	v_mfma_f32_16x16x32_bf16 v[112:115], v[196:199], v[164:167], v[112:115]
	v_mfma_f32_16x16x32_bf16 v[104:107], v[204:207], v[164:167], v[104:107]
	v_mfma_f32_16x16x32_bf16 v[96:99], v[196:199], v[172:175], v[96:99]
	v_mfma_f32_16x16x32_bf16 v[88:91], v[204:207], v[172:175], v[88:91]
	v_mfma_f32_16x16x32_bf16 v[80:83], v[196:199], v[180:183], v[80:83]
	v_mfma_f32_16x16x32_bf16 v[72:75], v[204:207], v[180:183], v[72:75]
	v_mfma_f32_16x16x32_bf16 v[68:71], v[196:199], v[188:191], v[68:71]
	v_mfma_f32_16x16x32_bf16 v[64:67], v[204:207], v[188:191], v[64:67]
	s_mov_b32 m0, s75
	v_lshl_add_u64 v[134:135], s[68:69], 0, v[132:133]
	s_barrier
	ds_read_b128 v[160:163], v139 offset:49152
	ds_read_b128 v[164:167], v139 offset:50176
	ds_read_b128 v[168:171], v139 offset:51200
	ds_read_b128 v[172:175], v139 offset:52224
	ds_read_b128 v[176:179], v139 offset:53248
	ds_read_b128 v[180:183], v139 offset:54272
	ds_read_b128 v[184:187], v139 offset:55296
	ds_read_b128 v[188:191], v139 offset:56320
	global_load_lds_dwordx4 v[134:135], off
	v_lshl_add_u64 v[134:135], s[68:69], 0, v[130:131]
	s_mov_b32 m0, s76
	s_nop 0
	global_load_lds_dwordx4 v[134:135], off
	s_barrier
; #define G_STAGE(bufoff, gbase, voff) do { _Pragma("unroll") for (int _i = 0; _i < 2; ++_i) \
;         __builtin_amdgcn_global_load_lds((const unsigned*)((const char*)(gbase) + (voff)[_i]), (LAS unsigned*)(lds + (bufoff) + ldsw + _i * 8192), 16, 0, 0); } while (0)
; #define G_MMA(ai, bj, At, Bt) do { __builtin_amdgcn_s_setprio(1); _Pragma("unroll") for (int m = 0; m < 4; ++m) _Pragma("unroll") for (int n = 0; n < 2; ++n) _Pragma("unroll") for (int k = 0; k < 2; ++k) \
;         acc[ai][bj][m][n] = __builtin_amdgcn_mfma_f32_16x16x32_bf16(Bt[n][k], At[m][k], acc[ai][bj][m][n], 0, 0, 0); __builtin_amdgcn_s_setprio(0); } while (0)
; #define G_WAIT_V(n) asm volatile("s_waitcnt vmcnt(" #n ")" ::: "memory")
; #define G_WAIT_L(n) asm volatile("s_waitcnt lgkmcnt(" #n ")" ::: "memory")
; #define G_BAR __builtin_amdgcn_s_barrier()
; #define G_SCHED __builtin_amdgcn_sched_barrier(0)
; template <class J>
; DI void gemm_phase(LAS unsigned char* lds, const J& job) {
;     ...
;       G_BAR; G_WAIT_L(0); G_MMA(1, 0, At, B0); G_BAR; G_SCHED;
;       G_STAGE(G_SB(1, 1), b3 + hstepB, voffB);
;       G_WAIT_V(6); G_BAR; G_MMA(1, 1, At, B1); G_BAR;
;     }
	s_waitcnt lgkmcnt(0)
	s_waitcnt lgkmcnt(0)
	v_mfma_f32_16x16x32_bf16 v[60:63], v[140:143], v[160:163], v[60:63]
	v_mfma_f32_16x16x32_bf16 v[56:59], v[152:155], v[160:163], v[56:59]
	v_mfma_f32_16x16x32_bf16 v[52:55], v[140:143], v[168:171], v[52:55]
	v_mfma_f32_16x16x32_bf16 v[44:47], v[152:155], v[168:171], v[44:47]
	v_mfma_f32_16x16x32_bf16 v[36:39], v[140:143], v[176:179], v[36:39]
	v_mfma_f32_16x16x32_bf16 v[28:31], v[152:155], v[176:179], v[28:31]
	v_mfma_f32_16x16x32_bf16 v[20:23], v[140:143], v[184:187], v[20:23]
	v_mfma_f32_16x16x32_bf16 v[12:15], v[152:155], v[184:187], v[12:15]
	v_mfma_f32_16x16x32_bf16 v[60:63], v[148:151], v[164:167], v[60:63]
	v_mfma_f32_16x16x32_bf16 v[56:59], v[156:159], v[164:167], v[56:59]
	v_mfma_f32_16x16x32_bf16 v[52:55], v[148:151], v[172:175], v[52:55]
	v_mfma_f32_16x16x32_bf16 v[44:47], v[156:159], v[172:175], v[44:47]
	v_mfma_f32_16x16x32_bf16 v[36:39], v[148:151], v[180:183], v[36:39]
	v_mfma_f32_16x16x32_bf16 v[28:31], v[156:159], v[180:183], v[28:31]
	v_mfma_f32_16x16x32_bf16 v[20:23], v[148:151], v[188:191], v[20:23]
	v_mfma_f32_16x16x32_bf16 v[12:15], v[156:159], v[188:191], v[12:15]
	s_barrier
	s_add_u32 s66, s66, 0x20000
	s_addc_u32 s67, s67, 0
	s_add_i32 s0, s1, s24
	v_lshl_add_u64 v[134:135], s[66:67], 0, v[146:147]
	s_mov_b32 m0, s0
	s_nop 0
	global_load_lds_dwordx4 v[134:135], off
	v_lshl_add_u64 v[134:135], s[66:67], 0, v[128:129]
	s_add_i32 m0, s0, 0x2000
	s_nop 0
	global_load_lds_dwordx4 v[134:135], off
	s_waitcnt vmcnt(6)
	s_barrier
	v_mfma_f32_16x16x32_bf16 v[48:51], v[192:195], v[160:163], v[48:51]
	v_mfma_f32_16x16x32_bf16 v[40:43], v[200:203], v[160:163], v[40:43]
	v_mfma_f32_16x16x32_bf16 v[32:35], v[192:195], v[168:171], v[32:35]
	v_mfma_f32_16x16x32_bf16 v[24:27], v[200:203], v[168:171], v[24:27]
	v_mfma_f32_16x16x32_bf16 v[16:19], v[192:195], v[176:179], v[16:19]
	v_mfma_f32_16x16x32_bf16 v[8:11], v[200:203], v[176:179], v[8:11]
	v_mfma_f32_16x16x32_bf16 v[4:7], v[192:195], v[184:187], v[4:7]
	v_mfma_f32_16x16x32_bf16 v[0:3], v[200:203], v[184:187], v[0:3]
	v_mfma_f32_16x16x32_bf16 v[48:51], v[196:199], v[164:167], v[48:51]
	v_mfma_f32_16x16x32_bf16 v[40:43], v[204:207], v[164:167], v[40:43]
	v_mfma_f32_16x16x32_bf16 v[32:35], v[196:199], v[172:175], v[32:35]
	v_mfma_f32_16x16x32_bf16 v[24:27], v[204:207], v[172:175], v[24:27]
	v_mfma_f32_16x16x32_bf16 v[16:19], v[196:199], v[180:183], v[16:19]
	v_mfma_f32_16x16x32_bf16 v[8:11], v[204:207], v[180:183], v[8:11]
	v_mfma_f32_16x16x32_bf16 v[4:7], v[196:199], v[188:191], v[4:7]
	v_mfma_f32_16x16x32_bf16 v[0:3], v[204:207], v[188:191], v[0:3]
	s_add_i32 s6, s6, 2
	s_addk_i32 s56, 0x100
	s_addk_i32 s7, 0x100
	s_cmp_gt_u32 s6, 5
	s_barrier
	s_cbranch_scc0 .LBB0_104
; DI unsigned pk2(float lo, float hi) { unsigned r; asm("v_cvt_pk_bf16_f32 %0, %1, %2" : "=v"(r) : "v"(lo), "v"(hi)); return r; }
; #define G_WAIT_V(n) asm volatile("s_waitcnt vmcnt(" #n ")" ::: "memory")
; #define G_BAR __builtin_amdgcn_s_barrier()
; template <class J>
; DI void gemm_phase(LAS unsigned char* lds, const J& job) {
;     ...
;     if (!has_next) break;
; #pragma unroll
;     for (int a = 0; a < 2; ++a)
; #pragma unroll
;       for (int b = 0; b < 2; ++b)
; #pragma unroll
;         for (int m = 0; m < 4; ++m)
; #pragma unroll
;           for (int n = 0; n < 2; ++n) acc[a][b][m][n] = (f32x4){0.f, 0.f, 0.f, 0.f};
;     cur = nxt; cA = nA; cB = nB; ++ui;
;   }
;   G_WAIT_V(0);
;   if (wr == 0) G_BAR;
;   DI void epi(const Acc& acc, const Unit& u, int wr, int wc, int fr, int fq) const {
; #pragma unroll
;     for (int ai = 0; ai < 2; ++ai)
; #pragma unroll
;       for (int m = 0; m < 4; ++m) {
;         const int row = u.pm * 256 + ai * HALF + wr * 64 + m * 16 + fr;
; #pragma unroll
;         for (int bj = 0; bj < 2; ++bj) {
;           const int col = u.pn * 256 + bj * HALF + wc * 32 + 8 * fq;
;           const f32x4 v0 = acc[ai][bj][m][0], v1 = acc[ai][bj][m][1];
;           u32x4 o; o.x = pk2(v0.x, v0.y); o.y = pk2(v0.z, v0.w); o.z = pk2(v1.x, v1.y); o.w = pk2(v1.z, v1.w);
;           *(u32x4*)(Z + (size_t)row * NGATE + col) = o;
;         }
;       }
;   }
	v_mov_b32_e32 v135, v137
	v_mov_b32_e32 v134, v136
	s_lshl_b32 s0, s22, 8
	s_add_i32 s0, s0, s44
	v_add_u32_e32 v134, s0, v134
	s_lshl_b32 s0, s46, 8
	s_or_b32 s0, s0, s45
	v_cvt_pk_bf16_f32 v68, v68, v69
	v_cvt_pk_bf16_f32 v69, v70, v71
	v_cvt_pk_bf16_f32 v70, v64, v65
	v_add_u32_e32 v64, 0x80, v134
	v_lshl_add_u32 v140, v135, 3, s0
	v_ashrrev_i32_e32 v135, 31, v134
	v_ashrrev_i32_e32 v65, 31, v64
	v_lshlrev_b64 v[142:143], 14, v[134:135]
	v_ashrrev_i32_e32 v141, 31, v140
	v_lshlrev_b64 v[64:65], 14, v[64:65]
	v_cvt_pk_bf16_f32 v124, v124, v125
	v_cvt_pk_bf16_f32 v125, v126, v127
	v_cvt_pk_bf16_f32 v126, v120, v121
	v_cvt_pk_bf16_f32 v127, v122, v123
	v_lshl_add_u64 v[122:123], s[26:27], 0, v[142:143]
	v_lshlrev_b64 v[120:121], 1, v[140:141]
	v_cvt_pk_bf16_f32 v112, v112, v113
	v_cvt_pk_bf16_f32 v113, v114, v115
	v_cvt_pk_bf16_f32 v114, v104, v105
	v_add_u32_e32 v104, 16, v134
	v_cvt_pk_bf16_f32 v60, v60, v61
	v_cvt_pk_bf16_f32 v61, v62, v63
	v_cvt_pk_bf16_f32 v62, v56, v57
	v_lshl_add_u64 v[56:57], s[26:27], 0, v[64:65]
	v_cvt_pk_bf16_f32 v48, v48, v49
	v_cvt_pk_bf16_f32 v49, v50, v51
	v_cvt_pk_bf16_f32 v50, v40, v41
	v_add_u32_e32 v40, 0x90, v134
	v_lshl_add_u64 v[122:123], v[122:123], 0, v[120:121]
	v_ashrrev_i32_e32 v105, 31, v104
	v_lshl_add_u64 v[56:57], v[56:57], 0, v[120:121]
	v_ashrrev_i32_e32 v41, 31, v40
	v_cvt_pk_bf16_f32 v115, v106, v107
	global_store_dwordx4 v[122:123], v[112:115], off offset:256
	v_cvt_pk_bf16_f32 v51, v42, v43
	global_store_dwordx4 v[56:57], v[48:51], off offset:256
	v_cvt_pk_bf16_f32 v106, v108, v109
	v_cvt_pk_bf16_f32 v96, v96, v97
	v_cvt_pk_bf16_f32 v97, v98, v99
	s_nop 0
	v_lshlrev_b64 v[112:113], 14, v[104:105]
	v_lshl_add_u64 v[108:109], s[26:27], 0, v[112:113]
	v_lshlrev_b64 v[48:49], 14, v[40:41]
	v_cvt_pk_bf16_f32 v98, v88, v89
	v_add_u32_e32 v88, 32, v134
	v_cvt_pk_bf16_f32 v42, v44, v45
	v_lshl_add_u64 v[44:45], s[26:27], 0, v[48:49]
	v_cvt_pk_bf16_f32 v32, v32, v33
	v_cvt_pk_bf16_f32 v33, v34, v35
	v_cvt_pk_bf16_f32 v34, v24, v25
	v_add_u32_e32 v24, 0xa0, v134
	v_lshl_add_u64 v[108:109], v[108:109], 0, v[120:121]
	v_ashrrev_i32_e32 v89, 31, v88
	v_lshl_add_u64 v[44:45], v[44:45], 0, v[120:121]
	v_ashrrev_i32_e32 v25, 31, v24
	v_cvt_pk_bf16_f32 v99, v90, v91
	global_store_dwordx4 v[108:109], v[96:99], off offset:256
	v_cvt_pk_bf16_f32 v35, v26, v27
	global_store_dwordx4 v[44:45], v[32:35], off offset:256
	v_cvt_pk_bf16_f32 v90, v92, v93
	v_cvt_pk_bf16_f32 v80, v80, v81
	v_cvt_pk_bf16_f32 v81, v82, v83
	s_nop 0
	v_lshlrev_b64 v[96:97], 14, v[88:89]
	v_lshl_add_u64 v[92:93], s[26:27], 0, v[96:97]
	v_lshlrev_b64 v[32:33], 14, v[24:25]
	v_cvt_pk_bf16_f32 v82, v72, v73
	v_add_u32_e32 v72, 48, v134
	v_cvt_pk_bf16_f32 v26, v28, v29
	v_lshl_add_u64 v[28:29], s[26:27], 0, v[32:33]
	v_cvt_pk_bf16_f32 v16, v16, v17
	v_cvt_pk_bf16_f32 v17, v18, v19
	v_cvt_pk_bf16_f32 v18, v8, v9
	v_add_u32_e32 v8, 0xb0, v134
	v_lshl_add_u64 v[92:93], v[92:93], 0, v[120:121]
	v_ashrrev_i32_e32 v73, 31, v72
	v_lshl_add_u64 v[28:29], v[28:29], 0, v[120:121]
	v_ashrrev_i32_e32 v9, 31, v8
	v_cvt_pk_bf16_f32 v83, v74, v75
	global_store_dwordx4 v[92:93], v[80:83], off offset:256
	v_cvt_pk_bf16_f32 v19, v10, v11
	global_store_dwordx4 v[28:29], v[16:19], off offset:256
	v_cvt_pk_bf16_f32 v74, v76, v77
	v_cvt_pk_bf16_f32 v10, v12, v13
	s_and_b64 vcc, exec, s[12:13]
	v_lshlrev_b64 v[80:81], 14, v[72:73]
	v_lshlrev_b64 v[16:17], 14, v[8:9]
	v_lshl_add_u64 v[76:77], s[26:27], 0, v[80:81]
	v_lshl_add_u64 v[12:13], s[26:27], 0, v[16:17]
	v_lshl_add_u64 v[76:77], v[76:77], 0, v[120:121]
	v_lshl_add_u64 v[12:13], v[12:13], 0, v[120:121]
	s_mov_b32 s46, s8
	s_mov_b32 s22, s16
	s_mov_b64 s[62:63], s[20:21]
	s_mov_b64 s[64:65], s[18:19]
	global_store_dwordx4 v[122:123], v[124:127], off
	v_cvt_pk_bf16_f32 v104, v116, v117
	v_cvt_pk_bf16_f32 v105, v118, v119
	v_cvt_pk_bf16_f32 v107, v110, v111
	global_store_dwordx4 v[108:109], v[104:107], off
	v_cvt_pk_bf16_f32 v88, v100, v101
	v_cvt_pk_bf16_f32 v89, v102, v103
	v_cvt_pk_bf16_f32 v91, v94, v95
	global_store_dwordx4 v[92:93], v[88:91], off
	v_cvt_pk_bf16_f32 v72, v84, v85
	v_cvt_pk_bf16_f32 v73, v86, v87
	v_cvt_pk_bf16_f32 v75, v78, v79
	global_store_dwordx4 v[76:77], v[72:75], off
	v_cvt_pk_bf16_f32 v71, v66, v67
	global_store_dwordx4 v[76:77], v[68:71], off offset:256
	v_cvt_pk_bf16_f32 v63, v58, v59
	global_store_dwordx4 v[56:57], v[60:63], off
	v_cvt_pk_bf16_f32 v40, v52, v53
	v_cvt_pk_bf16_f32 v41, v54, v55
	v_cvt_pk_bf16_f32 v43, v46, v47
	global_store_dwordx4 v[44:45], v[40:43], off
	v_cvt_pk_bf16_f32 v24, v36, v37
	v_cvt_pk_bf16_f32 v25, v38, v39
	v_cvt_pk_bf16_f32 v27, v30, v31
	global_store_dwordx4 v[28:29], v[24:27], off
	v_cvt_pk_bf16_f32 v8, v20, v21
	v_cvt_pk_bf16_f32 v9, v22, v23
	v_cvt_pk_bf16_f32 v11, v14, v15
	global_store_dwordx4 v[12:13], v[8:11], off
	v_cvt_pk_bf16_f32 v4, v4, v5
	v_cvt_pk_bf16_f32 v5, v6, v7
	v_cvt_pk_bf16_f32 v6, v0, v1
	v_cvt_pk_bf16_f32 v7, v2, v3
	global_store_dwordx4 v[12:13], v[4:7], off offset:256
	s_cbranch_vccz .LBB0_101
	s_setprio 0
	s_waitcnt vmcnt(0)
	v_readlane_b32 s44, v255, 6
	s_cmpk_gt_u32 s4, 0xff
	v_readlane_b32 s45, v255, 7
	s_cbranch_scc1 .LBB0_108
	s_barrier

; DI int my_tid() { int t = threadIdx.x; asm volatile("" : "+v"(t)); return t; }
; DI int my_block() { int b = blockIdx.x; asm volatile("" : "+s"(b)); return b; }
; #define G_STAGE(bufoff, gbase, voff) do { _Pragma("unroll") for (int _i = 0; _i < 2; ++_i) \
;         __builtin_amdgcn_global_load_lds((const unsigned*)((const char*)(gbase) + (voff)[_i]), (LAS unsigned*)(lds + (bufoff) + ldsw + _i * 8192), 16, 0, 0); } while (0)
; #define G_BAR __builtin_amdgcn_s_barrier()
;   DI int brow_of(int R) const { return (R & ~31) + perm32(R & 31); }
; template <class J>
; DI void gemm_phase(LAS unsigned char* lds, const J& job) {
;   const int tid = my_tid(), wid = __builtin_amdgcn_readfirstlane(tid >> 6), lane = tid & 63, wr = wid >> 2, wc = wid & 3, fr = lane & 15, fq = lane >> 4;
;   const int nt = job.nt;
;   unsigned voffA[2], voffB[2];
; #pragma unroll
;   for (int i = 0; i < 2; ++i) { int R, C; stage_rc(tid * 16 + i * 8192, R, C); const int Rb = job.brow_of(R);
;     voffA[i] = (unsigned)(R * job.lda + C) * 2u; voffB[i] = (unsigned)(Rb * job.ldb + C) * 2u; }
;   const size_t kstep = (size_t)(BK * 2);
;   const size_t hstepA = (size_t)HALF * job.lda * 2, hstepB = (size_t)job.bhalf_rows() * job.ldb * 2;
;   const unsigned ldsw = (unsigned)wid * 1024u;
;   const int aoff = lds_byte(wr * 64 + fr, fq * 8), boff = lds_byte(wc * 32 + fr, fq * 8);
;     ...
;   Unit cur, nxt; int ui = 0;
;   if (!job.next(0, cur)) return;
;   f32x4 acc[2][2][4][2];
; #pragma unroll
;   for (int a = 0; a < 2; ++a)
; #pragma unroll
;     for (int b = 0; b < 2; ++b)
; #pragma unroll
;       for (int m = 0; m < 4; ++m)
; #pragma unroll
;         for (int n = 0; n < 2; ++n) acc[a][b][m][n] = (f32x4){0.f, 0.f, 0.f, 0.f};
;   bf16x8 At[4][2], B0[2][2], B1[2][2];
;   const char* cA = job.aptr(cur); const char* cB = job.bptr(cur);
;   const int koff = (my_block() & 7) * (nt >> 3), kmask = nt - 1;
;     ...
;   G_STAGE(G_SB(0, 0), cB + G_KT(0), voffB); G_STAGE(G_SA(0, 0), cA + G_KT(0), voffA); G_STAGE(G_SB(0, 1), cB + hstepB + G_KT(0), voffB); G_STAGE(G_SA(0, 1), cA + hstepA + G_KT(0), voffA);
;   if (wr == 1) G_BAR;
; __global__ void __launch_bounds__(512, 2) mega(Params p_unused) {
;     ...
;         { JobProj j; j.nt = 32; j.lda = DM; j.ldb = DM; j.l = l; j.G = G; j.c = c; j.nunits = NPAN * 24;
;           j.h = h; j.winT = winT + (size_t)l * INW * DM; j.proj = pz; j.out = p.out;
;           gemm_phase(lds, j); }
.LBB0_274:
	v_readlane_b32 s0, v255, 14
	s_load_dwordx2 s[10:11], s[60:61], 0xc8
	v_readlane_b32 s1, v255, 15
	s_and_b64 s[6:7], s[0:1], exec
	s_cselect_b32 s0, 0x3800000, 0
	s_add_u32 s12, s50, s0
	s_addc_u32 s13, s51, 0
	s_andn2_b64 vcc, exec, s[16:17]
	s_cbranch_vccnz .LBB0_318
	v_bfe_i32 v3, v0, 27, 1
	v_lshlrev_b32_e32 v1, 4, v0
	v_lshrrev_b32_e32 v3, 22, v3
	v_add_u32_e32 v3, v1, v3
	v_and_b32_e32 v3, 0xfffffc00, v3
	v_ashrrev_i32_e32 v2, 31, v0
	v_sub_u32_e32 v3, v1, v3
	v_lshrrev_b32_e32 v2, 26, v2
	s_waitcnt vmcnt(0)
	v_lshrrev_b32_e32 v4, 4, v3
	v_add_u32_e32 v2, v0, v2
	v_bitop3_b32 v4, v4, v3, 32 bitop3:0x6c
	v_ashrrev_i32_e32 v3, 31, v3
	v_ashrrev_i32_e32 v2, 6, v2
	v_lshrrev_b32_e32 v3, 26, v3
	v_lshlrev_b32_e32 v5, 3, v2
	v_add_u32_e32 v3, v4, v3
	v_and_b32_e32 v5, -16, v5
	v_ashrrev_i32_e32 v3, 6, v3
	v_add_u32_e32 v5, v3, v5
	v_mul_i32_i24_e32 v3, 64, v3
	v_sub_u32_e32 v3, v4, v3
	v_lshlrev_b32_e32 v2, 5, v2
	v_ashrrev_i16_sdwa v3, v220, sext(v3) dst_sel:DWORD dst_unused:UNUSED_PAD src0_sel:DWORD src1_sel:BYTE_0
	v_lshlrev_b32_e32 v4, 1, v5
	v_lshrrev_b32_e32 v6, 2, v5
	v_and_b32_e32 v2, 32, v2
	v_bfe_i32 v3, v3, 0, 16
	v_and_b32_e32 v4, 24, v4
	v_and_b32_e32 v6, 4, v6
	v_and_b32_e32 v7, 0xfffe3, v5
	v_or3_b32 v4, v7, v6, v4
	v_add_lshl_u32 v2, v2, v3, 1
	v_add_u32_e32 v1, 0x2000, v1
	v_lshl_add_u32 v128, v5, 12, v2
	v_lshl_add_u32 v146, v4, 12, v2
	v_ashrrev_i32_e32 v2, 31, v1
	v_lshrrev_b32_e32 v2, 22, v2
	v_add_u32_e32 v2, v1, v2
	s_ashr_i32 s16, s4, 6
	s_ashr_i32 s9, s8, 31
	s_ashr_i32 s65, s64, 31
	s_ashr_i32 s6, s4, 8
	v_ashrrev_i32_e32 v2, 10, v2
	s_lshl_b32 s5, s16, 10
	s_lshl_b64 s[18:19], s[8:9], 20
	s_lshl_b64 s[14:15], s[64:65], 20
	v_mul_i32_i24_e32 v3, 0x400, v2
	s_add_u32 s66, s12, s14
	s_mov_b32 s7, s2
	v_sub_u32_e32 v1, v1, v3
	s_addc_u32 s67, s13, s15
	s_lshl_b32 s0, s7, 2
	v_lshrrev_b32_e32 v3, 4, v1
	s_and_b32 s0, s0, 28
	v_bitop3_b32 v1, v3, v1, 32 bitop3:0x6c
	s_lshl_b32 s14, s0, 7
	v_ashrrev_i32_e32 v4, 31, v1
	s_add_u32 s20, s66, s14
	v_lshrrev_b32_e32 v4, 26, v4
	s_addc_u32 s21, s67, 0
	s_add_i32 s15, s5, 0x100
	v_lshlrev_b32_e32 v3, 3, v2
	v_add_u32_e32 v4, v1, v4
	s_add_i32 m0, s15, 0x10000
	v_and_b32_e32 v3, -16, v3
	v_ashrrev_i32_e32 v5, 6, v4
	v_and_b32_e32 v4, 0xc0, v4
	global_load_lds_dwordx4 v146, s[20:21]
	s_add_i32 m0, s15, 0x12000
	v_add_u32_e32 v3, v5, v3
	v_sub_u32_e32 v1, v1, v4
	s_add_u32 s68, s58, s18
	v_lshlrev_b32_e32 v2, 5, v2
	v_ashrrev_i16_sdwa v1, v220, sext(v1) dst_sel:DWORD dst_unused:UNUSED_PAD src0_sel:DWORD src1_sel:BYTE_0
	v_lshlrev_b32_e32 v4, 1, v3
	v_lshrrev_b32_e32 v5, 2, v3
	s_addc_u32 s69, s59, s19
	v_and_b32_e32 v2, 32, v2
	v_bfe_i32 v1, v1, 0, 16
	v_and_b32_e32 v4, 24, v4
	v_and_b32_e32 v5, 4, v5
	v_and_b32_e32 v6, 0xfffe3, v3
	s_add_u32 s18, s68, s14
	v_or3_b32 v4, v6, v5, v4
	v_add_lshl_u32 v1, v2, v1, 1
	s_addc_u32 s19, s69, 0
	s_add_i32 s24, s15, 0x2000
	v_lshl_add_u32 v132, v4, 12, v1
	s_add_u32 s9, s66, 0x80000
	global_load_lds_dwordx4 v132, s[20:21]
	s_mov_b32 m0, s15
	s_addc_u32 s17, s67, 0
	v_lshl_add_u32 v130, v3, 12, v1
	global_load_lds_dwordx4 v128, s[18:19]
	s_mov_b32 m0, s24
	s_add_u32 s20, s9, s14
	global_load_lds_dwordx4 v130, s[18:19]
	s_addc_u32 s21, s17, 0
	s_add_i32 m0, s15, 0x14000
	v_writelane_b32 v255, s36, 20
	global_load_lds_dwordx4 v146, s[20:21]
	s_add_i32 m0, s15, 0x16000
	s_add_u32 s18, s18, 0x80000
	s_addc_u32 s19, s19, 0
	s_add_i32 s25, s15, 0x4000
	v_writelane_b32 v255, s37, 21
	global_load_lds_dwordx4 v132, s[20:21]
	s_mov_b32 m0, s25
	s_add_i32 s36, s15, 0x6000
	global_load_lds_dwordx4 v128, s[18:19]
	s_mov_b32 m0, s36
	s_cmp_lg_u32 s6, 1
	global_load_lds_dwordx4 v130, s[18:19]
	s_cbranch_scc1 .LBB0_277
	s_barrier
	s_setprio 1

; #define G_STAGE(bufoff, gbase, voff) do { _Pragma("unroll") for (int _i = 0; _i < 2; ++_i) \
;         __builtin_amdgcn_global_load_lds((const unsigned*)((const char*)(gbase) + (voff)[_i]), (LAS unsigned*)(lds + (bufoff) + ldsw + _i * 8192), 16, 0, 0); } while (0)
; #define G_LDA(dst, b, h) do { _Pragma("unroll") for (int m = 0; m < 4; ++m) _Pragma("unroll") for (int k = 0; k < 2; ++k) dst[m][k] = *(const LAS bf16x8*)(lds + G_SA(b, h) + aoff + m * 2048 + k * 1024); } while (0)
; #define G_LDB(dst, b, h) do { _Pragma("unroll") for (int n = 0; n < 2; ++n) _Pragma("unroll") for (int k = 0; k < 2; ++k) dst[n][k] = *(const LAS bf16x8*)(lds + G_SB(b, h) + boff + n * 2048 + k * 1024); } while (0)
; #define G_MMA(ai, bj, At, Bt) do { __builtin_amdgcn_s_setprio(1); _Pragma("unroll") for (int m = 0; m < 4; ++m) _Pragma("unroll") for (int n = 0; n < 2; ++n) _Pragma("unroll") for (int k = 0; k < 2; ++k) \
;         acc[ai][bj][m][n] = __builtin_amdgcn_mfma_f32_16x16x32_bf16(Bt[n][k], At[m][k], acc[ai][bj][m][n], 0, 0, 0); __builtin_amdgcn_s_setprio(0); } while (0)
; #define G_WAIT_L(n) asm volatile("s_waitcnt lgkmcnt(" #n ")" ::: "memory")
; #define G_BAR __builtin_amdgcn_s_barrier()
; #define G_SCHED __builtin_amdgcn_sched_barrier(0)
;   DI const char* aptr(const Unit& u) const { return (const char*)(h + (size_t)u.pm * 256 * DM); }
; template <class J>
; DI void gemm_phase(LAS unsigned char* lds, const J& job) {
;     ...
;     const bool has_next = job.next(ui + 1, nxt);
;     const char* nA = has_next ? job.aptr(nxt) : cA; const char* nB = has_next ? job.bptr(nxt) : cB;
;     for (int t = 0; t < nt; t += 2) {
;       const bool last = (t == nt - 2);
;       const char* a1 = cA + G_KT(t + 1);
;       const char* a2 = last ? nA + G_KT(0) : cA + G_KT(t + 2); const char* b2 = last ? nB + G_KT(0) : cB + G_KT(t + 2);
;       const char* a3 = last ? nA + G_KT(1) : cA + G_KT(t + 3); const char* b3 = last ? nB + G_KT(1) : cB + G_KT(t + 3);
;       G_LDB(B0, 0, 0); G_SCHED; G_LDA(At, 0, 0); G_STAGE(G_SA(1, 1), a1 + hstepA, voffA);
;       G_WAIT_L(8); G_BAR; G_WAIT_L(0); G_MMA(0, 0, At, B0); G_BAR; G_SCHED;
;       G_LDB(B1, 0, 1); G_STAGE(G_SB(0, 0), b2, voffB);
;       G_BAR; G_WAIT_L(0); G_MMA(0, 1, At, B1); G_BAR;
;       G_LDA(At, 0, 1); G_STAGE(G_SA(0, 0), a2, voffA);
;       G_BAR; G_WAIT_L(0); G_MMA(1, 0, At, B0); G_BAR; G_SCHED;
.LBB0_282:
	s_add_i32 s1, s56, 0xffffff80
	s_and_b32 s0, s7, 0xf80
	s_and_b32 s1, s1, 0xf00
	s_add_u32 s10, s68, s1
	s_addc_u32 s11, s69, 0
	s_add_u32 s1, s66, s1
	s_addc_u32 s57, s67, 0
	s_and_b32 s70, s56, 0xf80
	s_add_u32 s71, s68, s70
	s_addc_u32 s72, s69, 0
	s_add_u32 s70, s66, s70
	s_addc_u32 s80, s67, 0
	s_cmp_eq_u32 s6, 28
	s_cselect_b32 s75, s46, s11
	s_cselect_b32 s74, s21, s10
	s_cselect_b32 s77, s96, s57
	s_cselect_b32 s76, s47, s1
	s_cselect_b32 s73, s97, s72
	s_cselect_b32 s72, s33, s71
	s_cselect_b32 s71, vcc_hi, s80
	s_cselect_b32 s70, vcc_lo, s70
	s_add_i32 s1, s84, 0x100
	v_add_u32_e32 v142, s1, v150
	ds_read_b128 v[134:137], v142
	ds_read_b128 v[138:141], v142 offset:1024
	ds_read_b128 v[152:155], v142 offset:2048
	ds_read_b128 v[156:159], v142 offset:3072
	s_add_u32 s10, s9, s0
	s_addc_u32 s11, s19, 0
	v_lshl_add_u64 v[142:143], s[10:11], 0, v[128:129]
	s_add_i32 m0, s15, 0xc000
	ds_read_b128 v[160:163], v151
	ds_read_b128 v[164:167], v151 offset:1024
	ds_read_b128 v[168:171], v151 offset:2048
	ds_read_b128 v[172:175], v151 offset:3072
	ds_read_b128 v[176:179], v151 offset:4096
	ds_read_b128 v[180:183], v151 offset:5120
	ds_read_b128 v[184:187], v151 offset:6144
	ds_read_b128 v[188:191], v151 offset:7168
	global_load_lds_dwordx4 v[142:143], off
	v_lshl_add_u64 v[142:143], s[10:11], 0, v[130:131]
	s_add_i32 m0, s15, 0xe000
	s_nop 0
	global_load_lds_dwordx4 v[142:143], off
	s_waitcnt lgkmcnt(8)
	s_barrier
	s_waitcnt lgkmcnt(0)
	s_waitcnt lgkmcnt(0)
	v_mfma_f32_16x16x32_bf16 v[124:127], v[134:137], v[160:163], v[124:127]
	v_mfma_f32_16x16x32_bf16 v[120:123], v[152:155], v[160:163], v[120:123]
	v_mfma_f32_16x16x32_bf16 v[108:111], v[134:137], v[168:171], v[108:111]
	v_mfma_f32_16x16x32_bf16 v[104:107], v[152:155], v[168:171], v[104:107]
	v_mfma_f32_16x16x32_bf16 v[92:95], v[134:137], v[176:179], v[92:95]
	v_mfma_f32_16x16x32_bf16 v[88:91], v[152:155], v[176:179], v[88:91]
	v_mfma_f32_16x16x32_bf16 v[76:79], v[134:137], v[184:187], v[76:79]
	v_mfma_f32_16x16x32_bf16 v[72:75], v[152:155], v[184:187], v[72:75]
	v_mfma_f32_16x16x32_bf16 v[124:127], v[138:141], v[164:167], v[124:127]
	v_mfma_f32_16x16x32_bf16 v[120:123], v[156:159], v[164:167], v[120:123]
	v_mfma_f32_16x16x32_bf16 v[108:111], v[138:141], v[172:175], v[108:111]
	v_mfma_f32_16x16x32_bf16 v[104:107], v[156:159], v[172:175], v[104:107]
	v_mfma_f32_16x16x32_bf16 v[92:95], v[138:141], v[180:183], v[92:95]
	v_mfma_f32_16x16x32_bf16 v[88:91], v[156:159], v[180:183], v[88:91]
	v_mfma_f32_16x16x32_bf16 v[76:79], v[138:141], v[188:191], v[76:79]
	v_mfma_f32_16x16x32_bf16 v[72:75], v[156:159], v[188:191], v[72:75]
	s_barrier
	s_add_i32 s0, s85, 0x100
	v_add_u32_e32 v142, s0, v150
	s_add_i32 s1, s1, s5
	ds_read_b128 v[192:195], v142
	ds_read_b128 v[196:199], v142 offset:1024
	ds_read_b128 v[200:203], v142 offset:2048
	ds_read_b128 v[204:207], v142 offset:3072
	v_lshl_add_u64 v[142:143], s[76:77], 0, v[146:147]
	s_mov_b32 m0, s1
	s_nop 0
	global_load_lds_dwordx4 v[142:143], off
	v_lshl_add_u64 v[142:143], s[76:77], 0, v[132:133]
	s_add_i32 m0, s1, 0x2000
	s_nop 0
	global_load_lds_dwordx4 v[142:143], off
	s_barrier
	s_waitcnt lgkmcnt(0)
	s_waitcnt lgkmcnt(0)
	v_mfma_f32_16x16x32_bf16 v[116:119], v[192:195], v[160:163], v[116:119]
	v_mfma_f32_16x16x32_bf16 v[112:115], v[200:203], v[160:163], v[112:115]
	v_mfma_f32_16x16x32_bf16 v[100:103], v[192:195], v[168:171], v[100:103]
	v_mfma_f32_16x16x32_bf16 v[96:99], v[200:203], v[168:171], v[96:99]
	v_mfma_f32_16x16x32_bf16 v[84:87], v[192:195], v[176:179], v[84:87]
	v_mfma_f32_16x16x32_bf16 v[80:83], v[200:203], v[176:179], v[80:83]
	v_mfma_f32_16x16x32_bf16 v[68:71], v[192:195], v[184:187], v[68:71]
	v_mfma_f32_16x16x32_bf16 v[64:67], v[200:203], v[184:187], v[64:67]
	v_mfma_f32_16x16x32_bf16 v[116:119], v[196:199], v[164:167], v[116:119]
	v_mfma_f32_16x16x32_bf16 v[112:115], v[204:207], v[164:167], v[112:115]
	v_mfma_f32_16x16x32_bf16 v[100:103], v[196:199], v[172:175], v[100:103]
	v_mfma_f32_16x16x32_bf16 v[96:99], v[204:207], v[172:175], v[96:99]
	v_mfma_f32_16x16x32_bf16 v[84:87], v[196:199], v[180:183], v[84:87]
	v_mfma_f32_16x16x32_bf16 v[80:83], v[204:207], v[180:183], v[80:83]
	v_mfma_f32_16x16x32_bf16 v[68:71], v[196:199], v[188:191], v[68:71]
	v_mfma_f32_16x16x32_bf16 v[64:67], v[204:207], v[188:191], v[64:67]
	s_mov_b32 m0, s15
	v_lshl_add_u64 v[142:143], s[74:75], 0, v[128:129]
	s_barrier
	ds_read_b128 v[160:163], v151 offset:16384
	ds_read_b128 v[164:167], v151 offset:17408
	ds_read_b128 v[168:171], v151 offset:18432
	ds_read_b128 v[172:175], v151 offset:19456
	ds_read_b128 v[176:179], v151 offset:20480
	ds_read_b128 v[180:183], v151 offset:21504
	ds_read_b128 v[184:187], v151 offset:22528
	ds_read_b128 v[188:191], v151 offset:23552
	global_load_lds_dwordx4 v[142:143], off
	v_lshl_add_u64 v[142:143], s[74:75], 0, v[130:131]
	s_mov_b32 m0, s24
	s_nop 0
	global_load_lds_dwordx4 v[142:143], off
	s_barrier
	s_waitcnt lgkmcnt(0)
	s_waitcnt lgkmcnt(0)
	v_mfma_f32_16x16x32_bf16 v[60:63], v[134:137], v[160:163], v[60:63]
	v_mfma_f32_16x16x32_bf16 v[56:59], v[152:155], v[160:163], v[56:59]
	v_mfma_f32_16x16x32_bf16 v[44:47], v[134:137], v[168:171], v[44:47]
	v_mfma_f32_16x16x32_bf16 v[40:43], v[152:155], v[168:171], v[40:43]
	v_mfma_f32_16x16x32_bf16 v[28:31], v[134:137], v[176:179], v[28:31]
	v_mfma_f32_16x16x32_bf16 v[24:27], v[152:155], v[176:179], v[24:27]
	v_mfma_f32_16x16x32_bf16 v[12:15], v[134:137], v[184:187], v[12:15]
	v_mfma_f32_16x16x32_bf16 v[8:11], v[152:155], v[184:187], v[8:11]
	v_mfma_f32_16x16x32_bf16 v[60:63], v[138:141], v[164:167], v[60:63]
	v_mfma_f32_16x16x32_bf16 v[56:59], v[156:159], v[164:167], v[56:59]
	v_mfma_f32_16x16x32_bf16 v[44:47], v[138:141], v[172:175], v[44:47]
	v_mfma_f32_16x16x32_bf16 v[40:43], v[156:159], v[172:175], v[40:43]
	v_mfma_f32_16x16x32_bf16 v[28:31], v[138:141], v[180:183], v[28:31]
	v_mfma_f32_16x16x32_bf16 v[24:27], v[156:159], v[180:183], v[24:27]
	v_mfma_f32_16x16x32_bf16 v[12:15], v[138:141], v[188:191], v[12:15]
	v_mfma_f32_16x16x32_bf16 v[8:11], v[156:159], v[188:191], v[8:11]
	s_barrier
; #define G_STAGE(bufoff, gbase, voff) do { _Pragma("unroll") for (int _i = 0; _i < 2; ++_i) \
;         __builtin_amdgcn_global_load_lds((const unsigned*)((const char*)(gbase) + (voff)[_i]), (LAS unsigned*)(lds + (bufoff) + ldsw + _i * 8192), 16, 0, 0); } while (0)
; #define G_LDA(dst, b, h) do { _Pragma("unroll") for (int m = 0; m < 4; ++m) _Pragma("unroll") for (int k = 0; k < 2; ++k) dst[m][k] = *(const LAS bf16x8*)(lds + G_SA(b, h) + aoff + m * 2048 + k * 1024); } while (0)
; #define G_LDB(dst, b, h) do { _Pragma("unroll") for (int n = 0; n < 2; ++n) _Pragma("unroll") for (int k = 0; k < 2; ++k) dst[n][k] = *(const LAS bf16x8*)(lds + G_SB(b, h) + boff + n * 2048 + k * 1024); } while (0)
; #define G_MMA(ai, bj, At, Bt) do { __builtin_amdgcn_s_setprio(1); _Pragma("unroll") for (int m = 0; m < 4; ++m) _Pragma("unroll") for (int n = 0; n < 2; ++n) _Pragma("unroll") for (int k = 0; k < 2; ++k) \
;         acc[ai][bj][m][n] = __builtin_amdgcn_mfma_f32_16x16x32_bf16(Bt[n][k], At[m][k], acc[ai][bj][m][n], 0, 0, 0); __builtin_amdgcn_s_setprio(0); } while (0)
; #define G_WAIT_V(n) asm volatile("s_waitcnt vmcnt(" #n ")" ::: "memory")
; #define G_WAIT_L(n) asm volatile("s_waitcnt lgkmcnt(" #n ")" ::: "memory")
; #define G_BAR __builtin_amdgcn_s_barrier()
; #define G_SCHED __builtin_amdgcn_sched_barrier(0)
; template <class J>
; DI void gemm_phase(LAS unsigned char* lds, const J& job) {
;     ...
;       G_STAGE(G_SB(0, 1), b2 + hstepB, voffB);
;       G_WAIT_V(6); G_BAR; G_MMA(1, 1, At, B1); G_BAR;
;       G_LDB(B0, 1, 0); G_SCHED; G_LDA(At, 1, 0); G_STAGE(G_SA(0, 1), a2 + hstepA, voffA);
;       G_WAIT_L(8); G_BAR; G_WAIT_L(0); G_MMA(0, 0, At, B0); G_BAR; G_SCHED;
;       G_LDB(B1, 1, 1); G_STAGE(G_SB(1, 0), b3, voffB);
;       G_BAR; G_WAIT_L(0); G_MMA(0, 1, At, B1); G_BAR;
;       G_LDA(At, 1, 1); G_STAGE(G_SA(1, 0), a3, voffA);
	s_add_u32 s10, s76, 0x80000
	s_addc_u32 s11, s77, 0
	s_add_i32 s0, s0, s5
	v_lshl_add_u64 v[134:135], s[10:11], 0, v[146:147]
	s_mov_b32 m0, s0
	s_nop 0
	global_load_lds_dwordx4 v[134:135], off
	v_lshl_add_u64 v[134:135], s[10:11], 0, v[132:133]
	s_add_i32 m0, s0, 0x2000
	s_nop 0
	global_load_lds_dwordx4 v[134:135], off
	s_waitcnt vmcnt(6)
	s_barrier
	v_mfma_f32_16x16x32_bf16 v[52:55], v[192:195], v[160:163], v[52:55]
	v_mfma_f32_16x16x32_bf16 v[48:51], v[200:203], v[160:163], v[48:51]
	v_mfma_f32_16x16x32_bf16 v[36:39], v[192:195], v[168:171], v[36:39]
	v_mfma_f32_16x16x32_bf16 v[32:35], v[200:203], v[168:171], v[32:35]
	v_mfma_f32_16x16x32_bf16 v[20:23], v[192:195], v[176:179], v[20:23]
	v_mfma_f32_16x16x32_bf16 v[16:19], v[200:203], v[176:179], v[16:19]
	v_mfma_f32_16x16x32_bf16 v[4:7], v[192:195], v[184:187], v[4:7]
	v_mfma_f32_16x16x32_bf16 v[0:3], v[200:203], v[184:187], v[0:3]
	v_mfma_f32_16x16x32_bf16 v[52:55], v[196:199], v[164:167], v[52:55]
	v_mfma_f32_16x16x32_bf16 v[48:51], v[204:207], v[164:167], v[48:51]
	v_mfma_f32_16x16x32_bf16 v[36:39], v[196:199], v[172:175], v[36:39]
	v_mfma_f32_16x16x32_bf16 v[32:35], v[204:207], v[172:175], v[32:35]
	v_mfma_f32_16x16x32_bf16 v[20:23], v[196:199], v[180:183], v[20:23]
	v_mfma_f32_16x16x32_bf16 v[16:19], v[204:207], v[180:183], v[16:19]
	v_mfma_f32_16x16x32_bf16 v[4:7], v[196:199], v[188:191], v[4:7]
	v_mfma_f32_16x16x32_bf16 v[0:3], v[204:207], v[188:191], v[0:3]
	s_add_i32 s0, s88, 0x100
	v_add_u32_e32 v142, s0, v150
	s_barrier
	ds_read_b128 v[134:137], v142
	ds_read_b128 v[138:141], v142 offset:1024
	ds_read_b128 v[152:155], v142 offset:2048
	ds_read_b128 v[156:159], v142 offset:3072
	s_add_u32 s10, s74, 0x80000
	s_addc_u32 s11, s75, 0
	s_mov_b32 m0, s25
	v_lshl_add_u64 v[142:143], s[10:11], 0, v[128:129]
	ds_read_b128 v[160:163], v151 offset:32768
	ds_read_b128 v[164:167], v151 offset:33792
	ds_read_b128 v[168:171], v151 offset:34816
	ds_read_b128 v[172:175], v151 offset:35840
	ds_read_b128 v[176:179], v151 offset:36864
	ds_read_b128 v[180:183], v151 offset:37888
	ds_read_b128 v[184:187], v151 offset:38912
	ds_read_b128 v[188:191], v151 offset:39936
	global_load_lds_dwordx4 v[142:143], off
	v_lshl_add_u64 v[142:143], s[10:11], 0, v[130:131]
	s_mov_b32 m0, s36
	s_nop 0
	global_load_lds_dwordx4 v[142:143], off
	s_waitcnt lgkmcnt(8)
	s_barrier
	s_waitcnt lgkmcnt(0)
	s_waitcnt lgkmcnt(0)
	v_mfma_f32_16x16x32_bf16 v[124:127], v[134:137], v[160:163], v[124:127]
	v_mfma_f32_16x16x32_bf16 v[120:123], v[152:155], v[160:163], v[120:123]
	v_mfma_f32_16x16x32_bf16 v[108:111], v[134:137], v[168:171], v[108:111]
	v_mfma_f32_16x16x32_bf16 v[104:107], v[152:155], v[168:171], v[104:107]
	v_mfma_f32_16x16x32_bf16 v[92:95], v[134:137], v[176:179], v[92:95]
	v_mfma_f32_16x16x32_bf16 v[88:91], v[152:155], v[176:179], v[88:91]
	v_mfma_f32_16x16x32_bf16 v[76:79], v[134:137], v[184:187], v[76:79]
	v_mfma_f32_16x16x32_bf16 v[72:75], v[152:155], v[184:187], v[72:75]
	v_mfma_f32_16x16x32_bf16 v[124:127], v[138:141], v[164:167], v[124:127]
	v_mfma_f32_16x16x32_bf16 v[120:123], v[156:159], v[164:167], v[120:123]
	v_mfma_f32_16x16x32_bf16 v[108:111], v[138:141], v[172:175], v[108:111]
	v_mfma_f32_16x16x32_bf16 v[104:107], v[156:159], v[172:175], v[104:107]
	v_mfma_f32_16x16x32_bf16 v[92:95], v[138:141], v[180:183], v[92:95]
	v_mfma_f32_16x16x32_bf16 v[88:91], v[156:159], v[180:183], v[88:91]
	v_mfma_f32_16x16x32_bf16 v[76:79], v[138:141], v[188:191], v[76:79]
	v_mfma_f32_16x16x32_bf16 v[72:75], v[156:159], v[188:191], v[72:75]
	s_barrier
	s_add_i32 s1, s89, 0x100
	v_add_u32_e32 v142, s1, v150
	s_add_i32 s0, s0, s5
	ds_read_b128 v[192:195], v142
	ds_read_b128 v[196:199], v142 offset:1024
	ds_read_b128 v[200:203], v142 offset:2048
	ds_read_b128 v[204:207], v142 offset:3072
	v_lshl_add_u64 v[142:143], s[70:71], 0, v[146:147]
	s_mov_b32 m0, s0
	s_nop 0
	global_load_lds_dwordx4 v[142:143], off
	v_lshl_add_u64 v[142:143], s[70:71], 0, v[132:133]
	s_add_i32 m0, s0, 0x2000
	s_nop 0
	global_load_lds_dwordx4 v[142:143], off
	s_barrier
	s_waitcnt lgkmcnt(0)
	s_waitcnt lgkmcnt(0)
	v_mfma_f32_16x16x32_bf16 v[116:119], v[192:195], v[160:163], v[116:119]
	v_mfma_f32_16x16x32_bf16 v[112:115], v[200:203], v[160:163], v[112:115]
	v_mfma_f32_16x16x32_bf16 v[100:103], v[192:195], v[168:171], v[100:103]
	v_mfma_f32_16x16x32_bf16 v[96:99], v[200:203], v[168:171], v[96:99]
	v_mfma_f32_16x16x32_bf16 v[84:87], v[192:195], v[176:179], v[84:87]
	v_mfma_f32_16x16x32_bf16 v[80:83], v[200:203], v[176:179], v[80:83]
	v_mfma_f32_16x16x32_bf16 v[68:71], v[192:195], v[184:187], v[68:71]
	v_mfma_f32_16x16x32_bf16 v[64:67], v[200:203], v[184:187], v[64:67]
	v_mfma_f32_16x16x32_bf16 v[116:119], v[196:199], v[164:167], v[116:119]
	v_mfma_f32_16x16x32_bf16 v[112:115], v[204:207], v[164:167], v[112:115]
	v_mfma_f32_16x16x32_bf16 v[100:103], v[196:199], v[172:175], v[100:103]
	v_mfma_f32_16x16x32_bf16 v[96:99], v[204:207], v[172:175], v[96:99]
	v_mfma_f32_16x16x32_bf16 v[84:87], v[196:199], v[180:183], v[84:87]
	v_mfma_f32_16x16x32_bf16 v[80:83], v[204:207], v[180:183], v[80:83]
	v_mfma_f32_16x16x32_bf16 v[68:71], v[196:199], v[188:191], v[68:71]
	v_mfma_f32_16x16x32_bf16 v[64:67], v[204:207], v[188:191], v[64:67]
	s_mov_b32 m0, s45
	v_lshl_add_u64 v[142:143], s[72:73], 0, v[128:129]
	s_barrier
; DI unsigned pk2(float lo, float hi) { unsigned r; asm("v_cvt_pk_bf16_f32 %0, %1, %2" : "=v"(r) : "v"(lo), "v"(hi)); return r; }
; #define G_STAGE(bufoff, gbase, voff) do { _Pragma("unroll") for (int _i = 0; _i < 2; ++_i) \
;         __builtin_amdgcn_global_load_lds((const unsigned*)((const char*)(gbase) + (voff)[_i]), (LAS unsigned*)(lds + (bufoff) + ldsw + _i * 8192), 16, 0, 0); } while (0)
; #define G_MMA(ai, bj, At, Bt) do { __builtin_amdgcn_s_setprio(1); _Pragma("unroll") for (int m = 0; m < 4; ++m) _Pragma("unroll") for (int n = 0; n < 2; ++n) _Pragma("unroll") for (int k = 0; k < 2; ++k) \
;         acc[ai][bj][m][n] = __builtin_amdgcn_mfma_f32_16x16x32_bf16(Bt[n][k], At[m][k], acc[ai][bj][m][n], 0, 0, 0); __builtin_amdgcn_s_setprio(0); } while (0)
; #define G_WAIT_V(n) asm volatile("s_waitcnt vmcnt(" #n ")" ::: "memory")
; #define G_WAIT_L(n) asm volatile("s_waitcnt lgkmcnt(" #n ")" ::: "memory")
; #define G_BAR __builtin_amdgcn_s_barrier()
; #define G_SCHED __builtin_amdgcn_sched_barrier(0)
; template <class J>
; DI void gemm_phase(LAS unsigned char* lds, const J& job) {
;     ...
;       G_BAR; G_WAIT_L(0); G_MMA(1, 0, At, B0); G_BAR; G_SCHED;
;       G_STAGE(G_SB(1, 1), b3 + hstepB, voffB);
;       G_WAIT_V(6); G_BAR; G_MMA(1, 1, At, B1); G_BAR;
;     }
;   DI void epi(const Acc& acc, const Unit& u, int wr, int wc, int fr, int fq) const {
; #pragma unroll
;     for (int ai = 0; ai < 2; ++ai)
; #pragma unroll
;       for (int m = 0; m < 4; ++m) {
;         const int rl = ai * HALF + wr * 64 + m * 16 + fr;
; #pragma unroll
;         for (int bj = 0; bj < 2; ++bj) {
;           const int col = u.pn * 256 + bj * HALF + wc * 32 + 8 * fq;
;           const f32x4 v0 = acc[ai][bj][m][0], v1 = acc[ai][bj][m][1];
;           const int row = u.pm * 256 + rl;
;           u32x4 o; o.x = pk2(v0.x, v0.y); o.y = pk2(v0.z, v0.w); o.z = pk2(v1.x, v1.y); o.w = pk2(v1.z, v1.w);
;           *(u32x4*)(proj + (size_t)row * NPROJ + col) = o;
;           if (u.pn >= 8 && u.pn < 12) {
;             const int isv = u.pn >= 10; const int cc = col - (isv ? C_BV : C_BK);
;             float* dst = out + (isv ? O_VP : O_KP) + ((size_t)l * TP + row) * 512 + cc;
;             *(f32x4*)dst = v0; *(f32x4*)(dst + 4) = v1;
	ds_read_b128 v[160:163], v151 offset:49152
	ds_read_b128 v[164:167], v151 offset:50176
	ds_read_b128 v[168:171], v151 offset:51200
	ds_read_b128 v[172:175], v151 offset:52224
	ds_read_b128 v[176:179], v151 offset:53248
	ds_read_b128 v[180:183], v151 offset:54272
	ds_read_b128 v[184:187], v151 offset:55296
	ds_read_b128 v[188:191], v151 offset:56320
	global_load_lds_dwordx4 v[142:143], off
	v_lshl_add_u64 v[142:143], s[72:73], 0, v[130:131]
	s_mov_b32 m0, s65
	s_nop 0
	global_load_lds_dwordx4 v[142:143], off
	s_barrier
	s_waitcnt lgkmcnt(0)
	s_waitcnt lgkmcnt(0)
	v_mfma_f32_16x16x32_bf16 v[60:63], v[134:137], v[160:163], v[60:63]
	v_mfma_f32_16x16x32_bf16 v[56:59], v[152:155], v[160:163], v[56:59]
	v_mfma_f32_16x16x32_bf16 v[44:47], v[134:137], v[168:171], v[44:47]
	v_mfma_f32_16x16x32_bf16 v[40:43], v[152:155], v[168:171], v[40:43]
	v_mfma_f32_16x16x32_bf16 v[28:31], v[134:137], v[176:179], v[28:31]
	v_mfma_f32_16x16x32_bf16 v[24:27], v[152:155], v[176:179], v[24:27]
	v_mfma_f32_16x16x32_bf16 v[12:15], v[134:137], v[184:187], v[12:15]
	v_mfma_f32_16x16x32_bf16 v[8:11], v[152:155], v[184:187], v[8:11]
	v_mfma_f32_16x16x32_bf16 v[60:63], v[138:141], v[164:167], v[60:63]
	v_mfma_f32_16x16x32_bf16 v[56:59], v[156:159], v[164:167], v[56:59]
	v_mfma_f32_16x16x32_bf16 v[44:47], v[138:141], v[172:175], v[44:47]
	v_mfma_f32_16x16x32_bf16 v[40:43], v[156:159], v[172:175], v[40:43]
	v_mfma_f32_16x16x32_bf16 v[28:31], v[138:141], v[180:183], v[28:31]
	v_mfma_f32_16x16x32_bf16 v[24:27], v[156:159], v[180:183], v[24:27]
	v_mfma_f32_16x16x32_bf16 v[12:15], v[138:141], v[188:191], v[12:15]
	v_mfma_f32_16x16x32_bf16 v[8:11], v[156:159], v[188:191], v[8:11]
	s_barrier
	s_add_u32 s10, s70, 0x80000
	s_addc_u32 s11, s71, 0
	s_add_i32 s0, s1, s5
	v_lshl_add_u64 v[134:135], s[10:11], 0, v[146:147]
	s_mov_b32 m0, s0
	s_nop 0
	global_load_lds_dwordx4 v[134:135], off
	v_lshl_add_u64 v[134:135], s[10:11], 0, v[132:133]
	s_add_i32 m0, s0, 0x2000
	s_nop 0
	global_load_lds_dwordx4 v[134:135], off
	s_waitcnt vmcnt(6)
	s_barrier
	v_mfma_f32_16x16x32_bf16 v[52:55], v[192:195], v[160:163], v[52:55]
	v_mfma_f32_16x16x32_bf16 v[48:51], v[200:203], v[160:163], v[48:51]
	v_mfma_f32_16x16x32_bf16 v[36:39], v[192:195], v[168:171], v[36:39]
	v_mfma_f32_16x16x32_bf16 v[32:35], v[200:203], v[168:171], v[32:35]
	v_mfma_f32_16x16x32_bf16 v[20:23], v[192:195], v[176:179], v[20:23]
	v_mfma_f32_16x16x32_bf16 v[16:19], v[200:203], v[176:179], v[16:19]
	v_mfma_f32_16x16x32_bf16 v[4:7], v[192:195], v[184:187], v[4:7]
	v_mfma_f32_16x16x32_bf16 v[0:3], v[200:203], v[184:187], v[0:3]
	v_mfma_f32_16x16x32_bf16 v[52:55], v[196:199], v[164:167], v[52:55]
	v_mfma_f32_16x16x32_bf16 v[48:51], v[204:207], v[164:167], v[48:51]
	v_mfma_f32_16x16x32_bf16 v[36:39], v[196:199], v[172:175], v[36:39]
	v_mfma_f32_16x16x32_bf16 v[32:35], v[204:207], v[172:175], v[32:35]
	v_mfma_f32_16x16x32_bf16 v[20:23], v[196:199], v[180:183], v[20:23]
	v_mfma_f32_16x16x32_bf16 v[16:19], v[204:207], v[180:183], v[16:19]
	v_mfma_f32_16x16x32_bf16 v[4:7], v[196:199], v[188:191], v[4:7]
	v_mfma_f32_16x16x32_bf16 v[0:3], v[204:207], v[188:191], v[0:3]
	s_add_i32 s6, s6, 2
	s_addk_i32 s56, 0x100
	s_addk_i32 s7, 0x100
	s_cmp_gt_u32 s6, 29
	s_barrier
	s_cbranch_scc0 .LBB0_282
	v_mov_b32_e32 v135, v148
	v_mov_b32_e32 v134, v149
	s_lshl_b32 s0, s64, 8
	s_or_b32 s0, s0, s38
	v_lshl_add_u32 v134, v134, 3, s0
	s_lshl_b32 s0, s8, 8
	s_add_i32 s0, s0, s37
	v_add_u32_e32 v136, s0, v135
	s_and_b32 s0, s64, -4
	s_cmp_eq_u32 s0, 8
	s_cselect_b64 s[66:67], -1, 0
	s_cmp_gt_u32 s64, 9
	s_cselect_b64 s[6:7], -1, 0
	s_and_b64 s[6:7], s[6:7], exec
	s_movk_i32 s1, 0xf600
	v_mov_b64_e32 v[138:139], s[26:27]
	s_cselect_b32 s7, s1, 0xfffff800
	s_mov_b32 s1, 0x3040000
	v_ashrrev_i32_e32 v137, 31, v136
	v_mad_i64_i32 v[138:139], s[8:9], v136, s92, v[138:139]
	v_ashrrev_i32_e32 v135, 31, v134
	s_cselect_b32 s6, s1, 0x2040000
	s_cmp_lg_u32 s0, 8
	v_lshlrev_b64 v[140:141], 11, v[136:137]
	v_lshl_add_u64 v[142:143], v[134:135], 1, v[138:139]
	v_add_u32_e32 v138, s7, v134
	v_cvt_pk_bf16_f32 v152, v124, v125
	v_cvt_pk_bf16_f32 v153, v126, v127
	v_cvt_pk_bf16_f32 v154, v120, v121
	v_cvt_pk_bf16_f32 v155, v122, v123
	global_store_dwordx4 v[142:143], v[152:155], off
	s_cbranch_scc1 .LBB0_285
	s_lshl_b32 s0, s6, 2
	s_add_u32 s8, s83, s0
	s_addc_u32 s9, s86, 0
	v_lshl_add_u64 v[152:153], s[8:9], 0, v[140:141]
	v_ashrrev_i32_e32 v139, 31, v138
	v_lshl_add_u64 v[152:153], v[138:139], 2, v[152:153]
	global_store_dwordx4 v[152:153], v[124:127], off
	global_store_dwordx4 v[152:153], v[120:123], off offset:16

; #define G_WAIT_V(n) asm volatile("s_waitcnt vmcnt(" #n ")" ::: "memory")
; #define G_BAR __builtin_amdgcn_s_barrier()
; template <class J>
; DI void gemm_phase(LAS unsigned char* lds, const J& job) {
;     ...
;   G_WAIT_V(0);
;   if (wr == 0) G_BAR;
;   G_BAR;
.LBB0_315:
	s_setprio 0
	s_waitcnt vmcnt(0)
	v_readlane_b32 s44, v255, 6
	v_readlane_b32 s46, v255, 8
	v_readlane_b32 s76, v255, 10
	s_cmpk_gt_u32 s4, 0xff
	v_readlane_b32 s45, v255, 7
	v_readlane_b32 s47, v255, 9
	v_readlane_b32 s77, v255, 11
	v_readlane_b32 s33, v255, 12
	s_movk_i32 s78, 0x1000
	s_movk_i32 s79, 0x100
	s_movk_i32 s80, 0x110
	v_readlane_b32 s83, v255, 13
	s_movk_i32 s86, 0x9ff
	s_cbranch_scc1 .LBB0_317
	s_barrier
